# baseline (speedup 1.0000x reference)
; __device__ __forceinline__ void lds_barrier() { asm volatile("s_waitcnt lgkmcnt(0)" ::: "memory"); __builtin_amdgcn_s_barrier(); asm volatile("" ::: "memory"); }
; __device__ __forceinline__ void wkv_phase(const WkvT& W, unsigned char* lds) {
;     const int tid = threadIdx.x, lane = tid & 63, wave = tid >> 6;
;     float* sP = (float*)lds; float* sV = sP + 2 * 12288; float* sY = sV + 1024;
;     for (int unit = blockIdx.x; unit < 256; unit += gridDim.x) {
;         const int q = (unit >> 3) & 3, hb = (unit & 7) + 8 * (unit >> 5), b = hb >> 5, h = hb & 31;
;         const size_t rowbase = (size_t)b * SEQ; const int cbase = h * 64;
;         float kkc[4], kac[4], rkc[4]; WkvRaw raw;
; #pragma unroll
;         for (int e = 0; e < 4; ++e) { const int j = cbase + 4 * (tid & 15) + e; kkc[e] = W.kk[j]; kac[e] = W.ka[j]; rkc[e] = W.rk[j]; }
;         f32x2 S = {0.f, 0.f};
;         const int il = 2 * wave + (lane >> 5), jj = lane & 31;
;         __syncthreads();
;         wkv_issue(W, raw, rowbase, cbase, q, 0, tid);
;         wkv_stage(W, raw, rowbase, h, q, 0, tid, kkc, kac, rkc, sP, sV);
;         lds_barrier();
; #pragma unroll 2
;         for (int c = 0; c < 256; ++c) {
;             const int bi = c & 1, bo = bi * 12288, bn = (bi ^ 1) * 12288;
;             if (c + 1 < 256) wkv_issue(W, raw, rowbase, cbase, q, c + 1, tid);
;             {
;                 const float* pp = sP + bo + jj * 12;
;                 const float* pv = sV + bi * 512 + il;
;                 f32x4 nA = *(const f32x4*)pp, nB = *(const f32x4*)(pp + 4); f32x2 nr = *(const f32x2*)(pp + 8); float nv = pv[0];
;                 float yk0 = 0.f, yk1 = 0.f, ep = 0.f;
;                 const bool oddrow = (lane & 16) != 0;
.LBB0_1610:
	s_cmp_lt_i32 s84, 15
	s_cselect_b64 s[48:49], -1, 0
	s_and_b64 s[0:1], s[48:49], s[0:1]
	s_andn2_b64 vcc, exec, s[0:1]
	s_cbranch_vccnz .LBB0_1647
	v_readfirstlane_b32 s99, v0
	s_mov_b64 s[52:53], s[78:79]
	s_cmpk_gt_i32 s2, 0xff
	s_cbranch_scc1 .LBB0_1647
	s_add_u32 s54, s52, 0x3500000
	s_addc_u32 s55, s53, 0
	s_add_u32 s56, s52, 0x7500000
	s_addc_u32 s57, s53, 0
	s_add_u32 s68, s52, 0x19500000
	s_addc_u32 s69, s53, 0
	s_add_u32 s86, s52, 0xb500000
	s_addc_u32 s87, s53, 0
	s_add_u32 s88, s52, 0xf500000
	s_addc_u32 s89, s53, 0
	s_add_u32 s90, s52, 0x1e500000
	v_and_b32_e32 v18, 15, v0
	v_and_b32_e32 v4, 0x1f0, v0
	s_addc_u32 s91, s53, 0
	s_add_i32 s3, 0, 0x18000
	v_lshlrev_b32_e32 v4, 2, v4
	v_lshlrev_b32_e32 v5, 4, v18
	v_add3_u32 v15, s3, v4, v5
	v_lshrrev_b32_e32 v5, 3, v0
	v_and_b32_e32 v5, 60, v5
	v_and_b32_e32 v6, 16, v0
	v_and_b32_e32 v2, 31, v0
	v_lshrrev_b32_e32 v14, 4, v0
	v_lshlrev_b32_e32 v20, 2, v18
	v_add_u32_e32 v21, s3, v5
	v_cmp_ne_u32_e64 s[4:5], 0, v6
	v_lshlrev_b32_e32 v6, 6, v18
	s_add_i32 s3, 0, 0x19000
	v_lshlrev_b32_e32 v1, 2, v0
	v_mov_b32_e32 v17, 0
	v_mul_u32_u24_e32 v3, 0x60, v0
	v_mad_u32_u24 v19, v2, 48, 0
	v_cmp_eq_u32_e64 s[6:7], 31, v2
	s_waitcnt vmcnt(1)
	v_add3_u32 v29, s3, v6, v5
	v_add3_u32 v60, s3, v4, v20
	v_cmp_eq_u32_e64 s[10:11], 16, v2
	v_cmp_eq_u32_e64 s[12:13], 17, v2
	v_cmp_eq_u32_e64 s[14:15], 18, v2
	v_cmp_eq_u32_e64 s[16:17], 19, v2
	v_cmp_eq_u32_e64 s[18:19], 20, v2
	v_cmp_eq_u32_e64 s[20:21], 21, v2
	v_cmp_eq_u32_e64 s[22:23], 22, v2
	v_cmp_eq_u32_e64 s[24:25], 23, v2
	v_cmp_eq_u32_e64 s[26:27], 24, v2
	v_cmp_eq_u32_e64 s[28:29], 25, v2
	v_cmp_eq_u32_e64 s[30:31], 26, v2
	v_cmp_eq_u32_e64 s[34:35], 27, v2
	v_cmp_eq_u32_e64 s[36:37], 28, v2
	v_cmp_eq_u32_e64 s[38:39], 29, v2
	v_cmp_eq_u32_e64 s[40:41], 30, v2
	v_and_b32_e32 v243, 8, v0
	v_cmp_ne_u32_e64 s[10:11], 0, v243
	v_and_b32_e32 v243, 4, v0
	v_cmp_ne_u32_e64 s[12:13], 0, v243
	v_and_b32_e32 v243, 2, v0
	v_cmp_ne_u32_e64 s[14:15], 0, v243
	v_and_b32_e32 v243, 1, v0
	v_cmp_ne_u32_e64 s[16:17], 0, v243
	v_readfirstlane_b32 s99, v0
	v_mul_u32_u24_e32 v182, 0x60, v18
	v_and_b32_e32 v188, 8, v18
	v_mul_u32_u24_e32 v183, 0xc0, v18
	v_mad_u32_u24 v182, v188, 6, v182
	v_add_u32_e32 v183, 48, v183
	v_lshrrev_b32_e32 v188, 4, v0
	v_sub_u32_e32 v183, v183, v182
	v_lshlrev_b32_e32 v188, 2, v188
	v_add_u32_e32 v184, 0x10200, v182
	v_add_u32_e32 v186, 0x18000, v188
	v_add_u32_e32 v185, 0x10200, v183
	v_lshl_add_u32 v187, v18, 6, v188
	v_add_u32_e32 v187, 0x19000, v187
	v_add_u32_e32 v189, 0x400, v186
	v_add_u32_e32 v226, 0x800, v186
	v_add_u32_e32 v227, 0xc00, v186
	v_lshlrev_b32_e32 v2, 12, v14
	v_lshlrev_b32_e32 v4, 1, v18
	s_mov_b32 s3, 0x13500000
	v_and_b32_e32 v1, 60, v1
	v_cmp_gt_u32_e64 s[0:1], 4, v18
	s_mov_b32 s93, 0
	v_cmp_eq_u32_e64 s[8:9], 0, v18
	v_add_u32_e32 v61, 0x10200, v19
	v_add_u32_e32 v62, 0x10220, v19
	v_add_u32_e32 v63, 0x10210, v19
	v_add_u32_e32 v64, 0x10800, v19
	v_add_u32_e32 v65, 0x10820, v19
	v_add_u32_e32 v66, 0x10810, v19
	v_add_u32_e32 v67, 0x10e00, v19
	v_add_u32_e32 v68, 0x10e20, v19
	v_add_u32_e32 v69, 0x10e10, v19
	v_add_u32_e32 v70, 0x11400, v19
	v_add_u32_e32 v71, 0x11420, v19
	v_add_u32_e32 v72, 0x11410, v19
	v_add_u32_e32 v73, 0x11a00, v19
	v_add_u32_e32 v74, 0x11a20, v19
	v_add_u32_e32 v75, 0x11a10, v19
	v_add_u32_e32 v76, 0x12000, v19
	v_add_u32_e32 v77, 0x12020, v19
	v_add_u32_e32 v78, 0x12010, v19
	v_add_u32_e32 v79, 0x12600, v19
	v_add_u32_e32 v80, 0x12620, v19
	v_add_u32_e32 v81, 0x12610, v19
	v_add_u32_e32 v82, 0x12c00, v19
	v_add_u32_e32 v83, 0x12c20, v19
	v_add_u32_e32 v84, 0x12c10, v19
	v_add_u32_e32 v85, 0x13200, v19
	v_add_u32_e32 v86, 0x13220, v19
	v_add_u32_e32 v87, 0x13210, v19
	v_add_u32_e32 v88, 0x13800, v19
	v_add_u32_e32 v89, 0x13820, v19
	s_waitcnt vmcnt(0)
	v_add_u32_e32 v90, 0x13810, v19
	v_add_u32_e32 v91, 0x13e00, v19
	v_add_u32_e32 v92, 0x13e20, v19
	v_add_u32_e32 v93, 0x13e10, v19
	v_add_u32_e32 v94, 0x14400, v19
	v_add_u32_e32 v95, 0x14420, v19
	v_add_u32_e32 v96, 0x14410, v19
	v_add_u32_e32 v97, 0x14a00, v19
	v_add_u32_e32 v98, 0x14a20, v19
	v_add_u32_e32 v99, 0x14a10, v19
	v_add_u32_e32 v100, 0x15000, v19
	v_add_u32_e32 v101, 0x15020, v19
	v_add_u32_e32 v102, 0x15010, v19
	v_add_u32_e32 v103, 0x15600, v19
	v_add_u32_e32 v104, 0x15620, v19
	v_add_u32_e32 v105, 0x15610, v19
	v_add_u32_e32 v106, 0x15c00, v19
	v_add_u32_e32 v107, 0x15c20, v19
	v_add_u32_e32 v108, 0x15c10, v19
	v_add_u32_e32 v109, 0x16200, v19
	v_add_u32_e32 v110, 0x16220, v19
	v_add_u32_e32 v111, 0x16210, v19
	v_add_u32_e32 v112, 0x16800, v19
	v_add_u32_e32 v113, 0x16820, v19
	v_add_u32_e32 v114, 0x16810, v19
	v_add_u32_e32 v115, 0x16e00, v19
	v_add_u32_e32 v116, 0x16e20, v19
	v_add_u32_e32 v117, 0x16e10, v19
	v_add_u32_e32 v118, 0x17400, v19
	v_add_u32_e32 v119, 0x17420, v19
	v_add_u32_e32 v120, 0x17410, v19
	v_add_u32_e32 v121, 0x17a00, v19
	v_add_u32_e32 v122, 0x17a20, v19
	v_add_u32_e32 v123, 0x17a10, v19
	v_lshlrev_b32_e32 v22, 10, v14
	v_mov_b32_e32 v23, v17
	v_or_b32_e32 v24, 0x13520000, v2
	v_mov_b32_e32 v25, v17
	v_lshlrev_b32_e32 v26, 7, v14
	v_mov_b32_e32 v27, v17
	v_lshl_or_b32 v28, v18, 3, v2
	v_or3_b32 v30, v2, v4, s3
	v_mov_b32_e32 v31, v17
	s_mov_b32 s3, 0xf800000
	v_mov_b32_e32 v124, 0x260
	s_mov_b64 s[94:95], 0x40000
	v_add_u32_e32 v125, 0, v3
	s_mov_b32 s44, s2
	s_mov_b32 s45, s2
	s_branch .LBB0_1614

; __device__ __forceinline__ void wkv_phase(const WkvT& W, unsigned char* lds) {
;     ...
;                 const float* pp = sP + bo + jj * 12;
;                 const float* pv = sV + bi * 512 + il;
;                 f32x4 nA = *(const f32x4*)pp, nB = *(const f32x4*)(pp + 4); f32x2 nr = *(const f32x2*)(pp + 8); float nv = pv[0];
;                 float yk0 = 0.f, yk1 = 0.f, ep = 0.f;
;                 const bool oddrow = (lane & 16) != 0;
; #pragma unroll
;                 for (int t = 0; t < 32; ++t) {
;                     const f32x2 a2 = {nA[0], nA[1]}, w2 = {nA[2], nA[3]}, b2 = {nB[0], nB[1]}, k2 = {nB[2], nB[3]}, r2 = nr; const float v = nv;
;                     if (t + 1 < 32) { nA = *(const f32x4*)(pp + (t + 1) * 384); nB = *(const f32x4*)(pp + (t + 1) * 384 + 4); nr = *(const f32x2*)(pp + (t + 1) * 384 + 8); nv = pv[(t + 1) * 16]; }
;                     float S0 = S.x, S1 = S.y;
;                     float d = S0 * a2.x; d = __builtin_fmaf(S1, a2.y, d);
;                     float t0 = S0 * w2.x; t0 = __builtin_fmaf(v, k2.x, t0); asm volatile("" : "+v"(t0));
;                     float t1 = S1 * w2.y; t1 = __builtin_fmaf(v, k2.y, t1); asm volatile("" : "+v"(t1));
;                     float yprev; const float sa = wkv_reduce(d, ep, yprev);
;                     S0 = __builtin_fmaf(sa, b2.x, t0); asm volatile("" : "+v"(S0));
;                     S1 = __builtin_fmaf(sa, b2.y, t1); asm volatile("" : "+v"(S1));
;                     ep = S0 * r2.x; ep = __builtin_fmaf(S1, r2.y, ep);
;                     S.x = S0; S.y = S1;
;                     if (t >= 1) { const bool hit = oddrow && ((lane & 15) == ((t - 1) & 15)); if (t <= 16) yk0 = hit ? yprev : yk0; else yk1 = hit ? yprev : yk1; }
;                 }
.Lwkv4_b1_entry:
	s_bitcmp1_b32 s99, 8
	s_cbranch_scc1 .Lwkv4_b1_skip
	ds_read_b128 v[190:193], v182
	ds_read_b128 v[194:197], v182 offset:16
	ds_read_b64 v[228:229], v182 offset:32
	ds_read_b128 v[198:201], v183
	ds_read_b128 v[202:205], v183 offset:16
	ds_read_b64 v[230:231], v183 offset:32
	ds_read2_b32 v[240:241], v186 offset0:0 offset1:16
	ds_read_b128 v[206:209], v182 offset:1536
	ds_read_b128 v[210:213], v182 offset:1552
	ds_read_b64 v[232:233], v182 offset:1568
	ds_read_b128 v[214:217], v183 offset:1536
	ds_read_b128 v[218:221], v183 offset:1552
	ds_read_b64 v[234:235], v183 offset:1568
	s_waitcnt lgkmcnt(6)
	v_pk_mul_f32 v[150:151], v[142:143], v[190:191]
	v_pk_fma_f32 v[150:151], v[144:145], v[198:199], v[150:151]
	v_pk_mul_f32 v[146:147], v[142:143], v[192:193]
	v_add_f32_e32 v154, v150, v151
	v_pk_mul_f32 v[148:149], v[144:145], v[200:201]
	v_pk_fma_f32 v[146:147], v[240:241], v[196:197], v[146:147] op_sel:[0,0,0] op_sel_hi:[0,1,1]
	v_add_f32_dpp v154, v154, v154 quad_perm:[1,0,3,2] row_mask:0xf bank_mask:0xf bound_ctrl:1
	v_pk_fma_f32 v[148:149], v[240:241], v[204:205], v[148:149] op_sel:[0,0,0] op_sel_hi:[0,1,1]
	s_nop 0
	v_add_f32_dpp v154, v154, v154 quad_perm:[2,3,0,1] row_mask:0xf bank_mask:0xf bound_ctrl:1
	ds_read_b128 v[126:129], v182 offset:3072
	ds_read_b128 v[130:133], v182 offset:3088
	v_add_f32_dpp v154, v154, v154 row_half_mirror row_mask:0xf bank_mask:0xf bound_ctrl:1
	ds_read_b64 v[236:237], v182 offset:3104
	ds_read_b128 v[134:137], v183 offset:3072
	v_add_f32_dpp v154, v154, v154 row_mirror row_mask:0xf bank_mask:0xf bound_ctrl:1
	v_pk_fma_f32 v[146:147], v[154:155], v[194:195], v[146:147] op_sel_hi:[0,1,1]
	v_pk_fma_f32 v[148:149], v[154:155], v[202:203], v[148:149] op_sel_hi:[0,1,1]
	ds_read_b128 v[222:225], v183 offset:3088
	ds_read_b64 v[238:239], v183 offset:3104
	ds_read2_b32 v[242:243], v186 offset0:32 offset1:48
	s_waitcnt lgkmcnt(7)
	v_pk_mul_f32 v[150:151], v[146:147], v[206:207]
	v_pk_fma_f32 v[150:151], v[148:149], v[214:215], v[150:151]
	v_pk_mul_f32 v[152:153], v[146:147], v[228:229]
	v_add_f32_e32 v154, v150, v151
	v_pk_fma_f32 v[152:153], v[148:149], v[230:231], v[152:153]
	v_pk_mul_f32 v[142:143], v[146:147], v[208:209]
	v_add_f32_dpp v154, v154, v154 quad_perm:[1,0,3,2] row_mask:0xf bank_mask:0xf bound_ctrl:1
	v_pk_mul_f32 v[144:145], v[148:149], v[216:217]
	v_add_f32_e32 v156, v152, v153
	v_add_f32_dpp v154, v154, v154 quad_perm:[2,3,0,1] row_mask:0xf bank_mask:0xf bound_ctrl:1
	v_pk_fma_f32 v[142:143], v[240:241], v[212:213], v[142:143] op_sel:[1,0,0] op_sel_hi:[1,1,1]
	v_pk_fma_f32 v[144:145], v[240:241], v[220:221], v[144:145] op_sel:[1,0,0] op_sel_hi:[1,1,1]
	v_add_f32_dpp v154, v154, v154 row_half_mirror row_mask:0xf bank_mask:0xf bound_ctrl:1
	ds_read_b128 v[190:193], v182 offset:4608
	ds_read_b128 v[194:197], v182 offset:4624
	v_add_f32_dpp v154, v154, v154 row_mirror row_mask:0xf bank_mask:0xf bound_ctrl:1
	ds_read_b64 v[228:229], v182 offset:4640
	v_pk_fma_f32 v[142:143], v[154:155], v[210:211], v[142:143] op_sel_hi:[0,1,1]
	v_pk_fma_f32 v[144:145], v[154:155], v[218:219], v[144:145] op_sel_hi:[0,1,1]
	ds_read_b128 v[198:201], v183 offset:4608
	ds_read_b128 v[202:205], v183 offset:4624
	ds_read_b64 v[230:231], v183 offset:4640
	s_waitcnt lgkmcnt(6)
	v_pk_mul_f32 v[150:151], v[142:143], v[126:127]
	v_pk_fma_f32 v[150:151], v[144:145], v[134:135], v[150:151]
	v_pk_mul_f32 v[152:153], v[142:143], v[232:233]
	v_add_f32_e32 v154, v150, v151
	v_pk_fma_f32 v[152:153], v[144:145], v[234:235], v[152:153]
	v_pk_mul_f32 v[146:147], v[142:143], v[128:129]
	v_add_f32_dpp v154, v154, v154 quad_perm:[1,0,3,2] row_mask:0xf bank_mask:0xf bound_ctrl:1
	v_pk_mul_f32 v[148:149], v[144:145], v[136:137]
	v_add_f32_e32 v157, v152, v153
	v_add_f32_dpp v154, v154, v154 quad_perm:[2,3,0,1] row_mask:0xf bank_mask:0xf bound_ctrl:1
	v_pk_fma_f32 v[146:147], v[242:243], v[132:133], v[146:147] op_sel:[0,0,0] op_sel_hi:[0,1,1]
	v_pk_fma_f32 v[148:149], v[242:243], v[224:225], v[148:149] op_sel:[0,0,0] op_sel_hi:[0,1,1]
	v_add_f32_dpp v154, v154, v154 row_half_mirror row_mask:0xf bank_mask:0xf bound_ctrl:1
	ds_read_b128 v[206:209], v182 offset:6144
	ds_read_b128 v[210:213], v182 offset:6160
	v_add_f32_dpp v154, v154, v154 row_mirror row_mask:0xf bank_mask:0xf bound_ctrl:1
	ds_read_b64 v[232:233], v182 offset:6176
	ds_read_b128 v[214:217], v183 offset:6144
	v_pk_fma_f32 v[146:147], v[154:155], v[130:131], v[146:147] op_sel_hi:[0,1,1]
	v_pk_fma_f32 v[148:149], v[154:155], v[222:223], v[148:149] op_sel_hi:[0,1,1]
	ds_read_b128 v[218:221], v183 offset:6160
	ds_read_b64 v[234:235], v183 offset:6176
	ds_read2_b32 v[240:241], v186 offset0:64 offset1:80
	s_waitcnt lgkmcnt(7)
	v_pk_mul_f32 v[150:151], v[146:147], v[190:191]
	v_pk_fma_f32 v[150:151], v[148:149], v[198:199], v[150:151]
	v_pk_mul_f32 v[152:153], v[146:147], v[236:237]
	v_add_f32_e32 v154, v150, v151
	v_pk_fma_f32 v[152:153], v[148:149], v[238:239], v[152:153]
	v_pk_mul_f32 v[142:143], v[146:147], v[192:193]
	v_add_f32_dpp v154, v154, v154 quad_perm:[1,0,3,2] row_mask:0xf bank_mask:0xf bound_ctrl:1
	v_pk_mul_f32 v[144:145], v[148:149], v[200:201]
	v_add_f32_e32 v158, v152, v153
	v_add_f32_dpp v154, v154, v154 quad_perm:[2,3,0,1] row_mask:0xf bank_mask:0xf bound_ctrl:1
	v_pk_fma_f32 v[142:143], v[242:243], v[196:197], v[142:143] op_sel:[1,0,0] op_sel_hi:[1,1,1]
	v_pk_fma_f32 v[144:145], v[242:243], v[204:205], v[144:145] op_sel:[1,0,0] op_sel_hi:[1,1,1]
	v_add_f32_dpp v154, v154, v154 row_half_mirror row_mask:0xf bank_mask:0xf bound_ctrl:1
	ds_read_b128 v[126:129], v182 offset:7680
	ds_read_b128 v[130:133], v182 offset:7696
	v_add_f32_dpp v154, v154, v154 row_mirror row_mask:0xf bank_mask:0xf bound_ctrl:1
	ds_read_b64 v[236:237], v182 offset:7712
	v_pk_fma_f32 v[142:143], v[154:155], v[194:195], v[142:143] op_sel_hi:[0,1,1]
	v_pk_fma_f32 v[144:145], v[154:155], v[202:203], v[144:145] op_sel_hi:[0,1,1]
	ds_read_b128 v[134:137], v183 offset:7680
	ds_read_b128 v[222:225], v183 offset:7696
	ds_read_b64 v[238:239], v183 offset:7712
	s_waitcnt lgkmcnt(6)
; __device__ __forceinline__ void wkv_phase(const WkvT& W, unsigned char* lds) {
;     ...
;                 const float* pp = sP + bo + jj * 12;
;                 const float* pv = sV + bi * 512 + il;
;                 f32x4 nA = *(const f32x4*)pp, nB = *(const f32x4*)(pp + 4); f32x2 nr = *(const f32x2*)(pp + 8); float nv = pv[0];
;                 float yk0 = 0.f, yk1 = 0.f, ep = 0.f;
;                 const bool oddrow = (lane & 16) != 0;
; #pragma unroll
;                 for (int t = 0; t < 32; ++t) {
;                     const f32x2 a2 = {nA[0], nA[1]}, w2 = {nA[2], nA[3]}, b2 = {nB[0], nB[1]}, k2 = {nB[2], nB[3]}, r2 = nr; const float v = nv;
;                     if (t + 1 < 32) { nA = *(const f32x4*)(pp + (t + 1) * 384); nB = *(const f32x4*)(pp + (t + 1) * 384 + 4); nr = *(const f32x2*)(pp + (t + 1) * 384 + 8); nv = pv[(t + 1) * 16]; }
;                     float S0 = S.x, S1 = S.y;
;                     float d = S0 * a2.x; d = __builtin_fmaf(S1, a2.y, d);
;                     float t0 = S0 * w2.x; t0 = __builtin_fmaf(v, k2.x, t0); asm volatile("" : "+v"(t0));
;                     float t1 = S1 * w2.y; t1 = __builtin_fmaf(v, k2.y, t1); asm volatile("" : "+v"(t1));
;                     float yprev; const float sa = wkv_reduce(d, ep, yprev);
;                     S0 = __builtin_fmaf(sa, b2.x, t0); asm volatile("" : "+v"(S0));
;                     S1 = __builtin_fmaf(sa, b2.y, t1); asm volatile("" : "+v"(S1));
;                     ep = S0 * r2.x; ep = __builtin_fmaf(S1, r2.y, ep);
;                     S.x = S0; S.y = S1;
;                     if (t >= 1) { const bool hit = oddrow && ((lane & 15) == ((t - 1) & 15)); if (t <= 16) yk0 = hit ? yprev : yk0; else yk1 = hit ? yprev : yk1; }
;                 }
	v_pk_mul_f32 v[150:151], v[142:143], v[206:207]
	v_pk_fma_f32 v[150:151], v[144:145], v[214:215], v[150:151]
	v_pk_mul_f32 v[152:153], v[142:143], v[228:229]
	v_add_f32_e32 v154, v150, v151
	v_pk_fma_f32 v[152:153], v[144:145], v[230:231], v[152:153]
	v_pk_mul_f32 v[146:147], v[142:143], v[208:209]
	v_add_f32_dpp v154, v154, v154 quad_perm:[1,0,3,2] row_mask:0xf bank_mask:0xf bound_ctrl:1
	v_pk_mul_f32 v[148:149], v[144:145], v[216:217]
	v_add_f32_e32 v159, v152, v153
	v_add_f32_dpp v154, v154, v154 quad_perm:[2,3,0,1] row_mask:0xf bank_mask:0xf bound_ctrl:1
	v_pk_fma_f32 v[146:147], v[240:241], v[212:213], v[146:147] op_sel:[0,0,0] op_sel_hi:[0,1,1]
	v_pk_fma_f32 v[148:149], v[240:241], v[220:221], v[148:149] op_sel:[0,0,0] op_sel_hi:[0,1,1]
	v_add_f32_dpp v154, v154, v154 row_half_mirror row_mask:0xf bank_mask:0xf bound_ctrl:1
	ds_read_b128 v[190:193], v182 offset:9216
	ds_read_b128 v[194:197], v182 offset:9232
	v_add_f32_dpp v154, v154, v154 row_mirror row_mask:0xf bank_mask:0xf bound_ctrl:1
	ds_read_b64 v[228:229], v182 offset:9248
	ds_read_b128 v[198:201], v183 offset:9216
	v_pk_fma_f32 v[146:147], v[154:155], v[210:211], v[146:147] op_sel_hi:[0,1,1]
	v_pk_fma_f32 v[148:149], v[154:155], v[218:219], v[148:149] op_sel_hi:[0,1,1]
	ds_read_b128 v[202:205], v183 offset:9232
	ds_read_b64 v[230:231], v183 offset:9248
	ds_read2_b32 v[242:243], v186 offset0:96 offset1:112
	s_waitcnt lgkmcnt(7)
	v_pk_mul_f32 v[150:151], v[146:147], v[126:127]
	v_pk_fma_f32 v[150:151], v[148:149], v[134:135], v[150:151]
	v_pk_mul_f32 v[152:153], v[146:147], v[232:233]
	v_add_f32_e32 v154, v150, v151
	v_pk_fma_f32 v[152:153], v[148:149], v[234:235], v[152:153]
	v_pk_mul_f32 v[142:143], v[146:147], v[128:129]
	v_add_f32_dpp v154, v154, v154 quad_perm:[1,0,3,2] row_mask:0xf bank_mask:0xf bound_ctrl:1
	v_pk_mul_f32 v[144:145], v[148:149], v[136:137]
	v_add_f32_e32 v160, v152, v153
	v_add_f32_dpp v154, v154, v154 quad_perm:[2,3,0,1] row_mask:0xf bank_mask:0xf bound_ctrl:1
	v_pk_fma_f32 v[142:143], v[240:241], v[132:133], v[142:143] op_sel:[1,0,0] op_sel_hi:[1,1,1]
	v_pk_fma_f32 v[144:145], v[240:241], v[224:225], v[144:145] op_sel:[1,0,0] op_sel_hi:[1,1,1]
	v_add_f32_dpp v154, v154, v154 row_half_mirror row_mask:0xf bank_mask:0xf bound_ctrl:1
	ds_read_b128 v[206:209], v182 offset:10752
	ds_read_b128 v[210:213], v182 offset:10768
	v_add_f32_dpp v154, v154, v154 row_mirror row_mask:0xf bank_mask:0xf bound_ctrl:1
	ds_read_b64 v[232:233], v182 offset:10784
	v_pk_fma_f32 v[142:143], v[154:155], v[130:131], v[142:143] op_sel_hi:[0,1,1]
	v_pk_fma_f32 v[144:145], v[154:155], v[222:223], v[144:145] op_sel_hi:[0,1,1]
	ds_read_b128 v[214:217], v183 offset:10752
	ds_read_b128 v[218:221], v183 offset:10768
	ds_read_b64 v[234:235], v183 offset:10784
	s_waitcnt lgkmcnt(6)
	v_pk_mul_f32 v[150:151], v[142:143], v[190:191]
	v_pk_fma_f32 v[150:151], v[144:145], v[198:199], v[150:151]
	v_pk_mul_f32 v[152:153], v[142:143], v[236:237]
	v_add_f32_e32 v154, v150, v151
	v_pk_fma_f32 v[152:153], v[144:145], v[238:239], v[152:153]
	v_pk_mul_f32 v[146:147], v[142:143], v[192:193]
	v_add_f32_dpp v154, v154, v154 quad_perm:[1,0,3,2] row_mask:0xf bank_mask:0xf bound_ctrl:1
	v_pk_mul_f32 v[148:149], v[144:145], v[200:201]
	v_add_f32_e32 v161, v152, v153
	v_add_f32_dpp v154, v154, v154 quad_perm:[2,3,0,1] row_mask:0xf bank_mask:0xf bound_ctrl:1
	v_pk_fma_f32 v[146:147], v[242:243], v[196:197], v[146:147] op_sel:[0,0,0] op_sel_hi:[0,1,1]
	v_pk_fma_f32 v[148:149], v[242:243], v[204:205], v[148:149] op_sel:[0,0,0] op_sel_hi:[0,1,1]
	v_add_f32_dpp v154, v154, v154 row_half_mirror row_mask:0xf bank_mask:0xf bound_ctrl:1
	ds_read_b128 v[126:129], v182 offset:12288
	ds_read_b128 v[130:133], v182 offset:12304
	v_add_f32_dpp v154, v154, v154 row_mirror row_mask:0xf bank_mask:0xf bound_ctrl:1
	ds_read_b64 v[236:237], v182 offset:12320
	ds_read_b128 v[134:137], v183 offset:12288
	v_pk_fma_f32 v[146:147], v[154:155], v[194:195], v[146:147] op_sel_hi:[0,1,1]
	v_pk_fma_f32 v[148:149], v[154:155], v[202:203], v[148:149] op_sel_hi:[0,1,1]
	ds_read_b128 v[222:225], v183 offset:12304
	ds_read_b64 v[238:239], v183 offset:12320
	ds_read2_b32 v[240:241], v186 offset0:128 offset1:144
	s_waitcnt lgkmcnt(7)
	v_pk_mul_f32 v[150:151], v[146:147], v[206:207]
	v_pk_fma_f32 v[150:151], v[148:149], v[214:215], v[150:151]
	v_pk_mul_f32 v[152:153], v[146:147], v[228:229]
	v_add_f32_e32 v154, v150, v151
	v_pk_fma_f32 v[152:153], v[148:149], v[230:231], v[152:153]
	v_pk_mul_f32 v[142:143], v[146:147], v[208:209]
	v_add_f32_dpp v154, v154, v154 quad_perm:[1,0,3,2] row_mask:0xf bank_mask:0xf bound_ctrl:1
	v_pk_mul_f32 v[144:145], v[148:149], v[216:217]
	v_add_f32_e32 v162, v152, v153
	v_add_f32_dpp v154, v154, v154 quad_perm:[2,3,0,1] row_mask:0xf bank_mask:0xf bound_ctrl:1
	v_pk_fma_f32 v[142:143], v[242:243], v[212:213], v[142:143] op_sel:[1,0,0] op_sel_hi:[1,1,1]
	v_pk_fma_f32 v[144:145], v[242:243], v[220:221], v[144:145] op_sel:[1,0,0] op_sel_hi:[1,1,1]
	v_add_f32_dpp v154, v154, v154 row_half_mirror row_mask:0xf bank_mask:0xf bound_ctrl:1
	ds_read_b128 v[190:193], v182 offset:13824
	ds_read_b128 v[194:197], v182 offset:13840
	v_add_f32_dpp v154, v154, v154 row_mirror row_mask:0xf bank_mask:0xf bound_ctrl:1
	ds_read_b64 v[228:229], v182 offset:13856
	v_pk_fma_f32 v[142:143], v[154:155], v[210:211], v[142:143] op_sel_hi:[0,1,1]
	v_pk_fma_f32 v[144:145], v[154:155], v[218:219], v[144:145] op_sel_hi:[0,1,1]
	ds_read_b128 v[198:201], v183 offset:13824
	ds_read_b128 v[202:205], v183 offset:13840
	ds_read_b64 v[230:231], v183 offset:13856
	s_waitcnt lgkmcnt(6)
; __device__ __forceinline__ void wkv_phase(const WkvT& W, unsigned char* lds) {
;     ...
;                 const float* pp = sP + bo + jj * 12;
;                 const float* pv = sV + bi * 512 + il;
;                 f32x4 nA = *(const f32x4*)pp, nB = *(const f32x4*)(pp + 4); f32x2 nr = *(const f32x2*)(pp + 8); float nv = pv[0];
;                 float yk0 = 0.f, yk1 = 0.f, ep = 0.f;
;                 const bool oddrow = (lane & 16) != 0;
; #pragma unroll
;                 for (int t = 0; t < 32; ++t) {
;                     const f32x2 a2 = {nA[0], nA[1]}, w2 = {nA[2], nA[3]}, b2 = {nB[0], nB[1]}, k2 = {nB[2], nB[3]}, r2 = nr; const float v = nv;
;                     if (t + 1 < 32) { nA = *(const f32x4*)(pp + (t + 1) * 384); nB = *(const f32x4*)(pp + (t + 1) * 384 + 4); nr = *(const f32x2*)(pp + (t + 1) * 384 + 8); nv = pv[(t + 1) * 16]; }
;                     float S0 = S.x, S1 = S.y;
;                     float d = S0 * a2.x; d = __builtin_fmaf(S1, a2.y, d);
;                     float t0 = S0 * w2.x; t0 = __builtin_fmaf(v, k2.x, t0); asm volatile("" : "+v"(t0));
;                     float t1 = S1 * w2.y; t1 = __builtin_fmaf(v, k2.y, t1); asm volatile("" : "+v"(t1));
;                     float yprev; const float sa = wkv_reduce(d, ep, yprev);
;                     S0 = __builtin_fmaf(sa, b2.x, t0); asm volatile("" : "+v"(S0));
;                     S1 = __builtin_fmaf(sa, b2.y, t1); asm volatile("" : "+v"(S1));
;                     ep = S0 * r2.x; ep = __builtin_fmaf(S1, r2.y, ep);
;                     S.x = S0; S.y = S1;
;                     if (t >= 1) { const bool hit = oddrow && ((lane & 15) == ((t - 1) & 15)); if (t <= 16) yk0 = hit ? yprev : yk0; else yk1 = hit ? yprev : yk1; }
;                 }
	v_pk_mul_f32 v[150:151], v[142:143], v[126:127]
	v_pk_fma_f32 v[150:151], v[144:145], v[134:135], v[150:151]
	v_pk_mul_f32 v[152:153], v[142:143], v[232:233]
	v_add_f32_e32 v154, v150, v151
	v_pk_fma_f32 v[152:153], v[144:145], v[234:235], v[152:153]
	v_pk_mul_f32 v[146:147], v[142:143], v[128:129]
	v_add_f32_dpp v154, v154, v154 quad_perm:[1,0,3,2] row_mask:0xf bank_mask:0xf bound_ctrl:1
	v_pk_mul_f32 v[148:149], v[144:145], v[136:137]
	v_add_f32_e32 v163, v152, v153
	v_add_f32_dpp v154, v154, v154 quad_perm:[2,3,0,1] row_mask:0xf bank_mask:0xf bound_ctrl:1
	v_pk_fma_f32 v[146:147], v[240:241], v[132:133], v[146:147] op_sel:[0,0,0] op_sel_hi:[0,1,1]
	v_pk_fma_f32 v[148:149], v[240:241], v[224:225], v[148:149] op_sel:[0,0,0] op_sel_hi:[0,1,1]
	v_add_f32_dpp v154, v154, v154 row_half_mirror row_mask:0xf bank_mask:0xf bound_ctrl:1
	ds_read_b128 v[206:209], v182 offset:15360
	ds_read_b128 v[210:213], v182 offset:15376
	v_add_f32_dpp v154, v154, v154 row_mirror row_mask:0xf bank_mask:0xf bound_ctrl:1
	ds_read_b64 v[232:233], v182 offset:15392
	ds_read_b128 v[214:217], v183 offset:15360
	v_pk_fma_f32 v[146:147], v[154:155], v[130:131], v[146:147] op_sel_hi:[0,1,1]
	v_pk_fma_f32 v[148:149], v[154:155], v[222:223], v[148:149] op_sel_hi:[0,1,1]
	ds_read_b128 v[218:221], v183 offset:15376
	ds_read_b64 v[234:235], v183 offset:15392
	ds_read2_b32 v[242:243], v186 offset0:160 offset1:176
	s_waitcnt lgkmcnt(7)
	v_pk_mul_f32 v[150:151], v[146:147], v[190:191]
	v_pk_fma_f32 v[150:151], v[148:149], v[198:199], v[150:151]
	v_pk_mul_f32 v[152:153], v[146:147], v[236:237]
	v_add_f32_e32 v154, v150, v151
	v_pk_fma_f32 v[152:153], v[148:149], v[238:239], v[152:153]
	v_pk_mul_f32 v[142:143], v[146:147], v[192:193]
	v_add_f32_dpp v154, v154, v154 quad_perm:[1,0,3,2] row_mask:0xf bank_mask:0xf bound_ctrl:1
	v_pk_mul_f32 v[144:145], v[148:149], v[200:201]
	v_add_f32_e32 v164, v152, v153
	v_add_f32_dpp v154, v154, v154 quad_perm:[2,3,0,1] row_mask:0xf bank_mask:0xf bound_ctrl:1
	v_pk_fma_f32 v[142:143], v[240:241], v[196:197], v[142:143] op_sel:[1,0,0] op_sel_hi:[1,1,1]
	v_pk_fma_f32 v[144:145], v[240:241], v[204:205], v[144:145] op_sel:[1,0,0] op_sel_hi:[1,1,1]
	v_add_f32_dpp v154, v154, v154 row_half_mirror row_mask:0xf bank_mask:0xf bound_ctrl:1
	ds_read_b128 v[126:129], v182 offset:16896
	ds_read_b128 v[130:133], v182 offset:16912
	v_add_f32_dpp v154, v154, v154 row_mirror row_mask:0xf bank_mask:0xf bound_ctrl:1
	ds_read_b64 v[236:237], v182 offset:16928
	v_pk_fma_f32 v[142:143], v[154:155], v[194:195], v[142:143] op_sel_hi:[0,1,1]
	v_pk_fma_f32 v[144:145], v[154:155], v[202:203], v[144:145] op_sel_hi:[0,1,1]
	ds_read_b128 v[134:137], v183 offset:16896
	ds_read_b128 v[222:225], v183 offset:16912
	ds_read_b64 v[238:239], v183 offset:16928
	s_waitcnt lgkmcnt(6)
	v_pk_mul_f32 v[150:151], v[142:143], v[206:207]
	v_pk_fma_f32 v[150:151], v[144:145], v[214:215], v[150:151]
	v_pk_mul_f32 v[152:153], v[142:143], v[228:229]
	v_add_f32_e32 v154, v150, v151
	v_pk_fma_f32 v[152:153], v[144:145], v[230:231], v[152:153]
	v_pk_mul_f32 v[146:147], v[142:143], v[208:209]
	v_add_f32_dpp v154, v154, v154 quad_perm:[1,0,3,2] row_mask:0xf bank_mask:0xf bound_ctrl:1
	v_pk_mul_f32 v[148:149], v[144:145], v[216:217]
	v_add_f32_e32 v165, v152, v153
	v_add_f32_dpp v154, v154, v154 quad_perm:[2,3,0,1] row_mask:0xf bank_mask:0xf bound_ctrl:1
	v_pk_fma_f32 v[146:147], v[242:243], v[212:213], v[146:147] op_sel:[0,0,0] op_sel_hi:[0,1,1]
	v_pk_fma_f32 v[148:149], v[242:243], v[220:221], v[148:149] op_sel:[0,0,0] op_sel_hi:[0,1,1]
	v_add_f32_dpp v154, v154, v154 row_half_mirror row_mask:0xf bank_mask:0xf bound_ctrl:1
	ds_read_b128 v[190:193], v182 offset:18432
	ds_read_b128 v[194:197], v182 offset:18448
	v_add_f32_dpp v154, v154, v154 row_mirror row_mask:0xf bank_mask:0xf bound_ctrl:1
	ds_read_b64 v[228:229], v182 offset:18464
	ds_read_b128 v[198:201], v183 offset:18432
	v_pk_fma_f32 v[146:147], v[154:155], v[210:211], v[146:147] op_sel_hi:[0,1,1]
	v_pk_fma_f32 v[148:149], v[154:155], v[218:219], v[148:149] op_sel_hi:[0,1,1]
	ds_read_b128 v[202:205], v183 offset:18448
	ds_read_b64 v[230:231], v183 offset:18464
	ds_read2_b32 v[240:241], v186 offset0:192 offset1:208
	s_waitcnt lgkmcnt(7)
	v_pk_mul_f32 v[150:151], v[146:147], v[126:127]
	v_pk_fma_f32 v[150:151], v[148:149], v[134:135], v[150:151]
	v_pk_mul_f32 v[152:153], v[146:147], v[232:233]
	v_add_f32_e32 v154, v150, v151
	v_pk_fma_f32 v[152:153], v[148:149], v[234:235], v[152:153]
	v_pk_mul_f32 v[142:143], v[146:147], v[128:129]
	v_add_f32_dpp v154, v154, v154 quad_perm:[1,0,3,2] row_mask:0xf bank_mask:0xf bound_ctrl:1
	v_pk_mul_f32 v[144:145], v[148:149], v[136:137]
	v_add_f32_e32 v166, v152, v153
	v_add_f32_dpp v154, v154, v154 quad_perm:[2,3,0,1] row_mask:0xf bank_mask:0xf bound_ctrl:1
	v_pk_fma_f32 v[142:143], v[242:243], v[132:133], v[142:143] op_sel:[1,0,0] op_sel_hi:[1,1,1]
	v_pk_fma_f32 v[144:145], v[242:243], v[224:225], v[144:145] op_sel:[1,0,0] op_sel_hi:[1,1,1]
	v_add_f32_dpp v154, v154, v154 row_half_mirror row_mask:0xf bank_mask:0xf bound_ctrl:1
	ds_read_b128 v[206:209], v182 offset:19968
	ds_read_b128 v[210:213], v182 offset:19984
	v_add_f32_dpp v154, v154, v154 row_mirror row_mask:0xf bank_mask:0xf bound_ctrl:1
	ds_read_b64 v[232:233], v182 offset:20000
	v_pk_fma_f32 v[142:143], v[154:155], v[130:131], v[142:143] op_sel_hi:[0,1,1]
	v_pk_fma_f32 v[144:145], v[154:155], v[222:223], v[144:145] op_sel_hi:[0,1,1]
	ds_read_b128 v[214:217], v183 offset:19968
	ds_read_b128 v[218:221], v183 offset:19984
	ds_read_b64 v[234:235], v183 offset:20000
	s_waitcnt lgkmcnt(6)
; __device__ __forceinline__ void wkv_phase(const WkvT& W, unsigned char* lds) {
;     ...
;                 const float* pp = sP + bo + jj * 12;
;                 const float* pv = sV + bi * 512 + il;
;                 f32x4 nA = *(const f32x4*)pp, nB = *(const f32x4*)(pp + 4); f32x2 nr = *(const f32x2*)(pp + 8); float nv = pv[0];
;                 float yk0 = 0.f, yk1 = 0.f, ep = 0.f;
;                 const bool oddrow = (lane & 16) != 0;
; #pragma unroll
;                 for (int t = 0; t < 32; ++t) {
;                     const f32x2 a2 = {nA[0], nA[1]}, w2 = {nA[2], nA[3]}, b2 = {nB[0], nB[1]}, k2 = {nB[2], nB[3]}, r2 = nr; const float v = nv;
;                     if (t + 1 < 32) { nA = *(const f32x4*)(pp + (t + 1) * 384); nB = *(const f32x4*)(pp + (t + 1) * 384 + 4); nr = *(const f32x2*)(pp + (t + 1) * 384 + 8); nv = pv[(t + 1) * 16]; }
;                     float S0 = S.x, S1 = S.y;
;                     float d = S0 * a2.x; d = __builtin_fmaf(S1, a2.y, d);
;                     float t0 = S0 * w2.x; t0 = __builtin_fmaf(v, k2.x, t0); asm volatile("" : "+v"(t0));
;                     float t1 = S1 * w2.y; t1 = __builtin_fmaf(v, k2.y, t1); asm volatile("" : "+v"(t1));
;                     float yprev; const float sa = wkv_reduce(d, ep, yprev);
;                     S0 = __builtin_fmaf(sa, b2.x, t0); asm volatile("" : "+v"(S0));
;                     S1 = __builtin_fmaf(sa, b2.y, t1); asm volatile("" : "+v"(S1));
;                     ep = S0 * r2.x; ep = __builtin_fmaf(S1, r2.y, ep);
;                     S.x = S0; S.y = S1;
;                     if (t >= 1) { const bool hit = oddrow && ((lane & 15) == ((t - 1) & 15)); if (t <= 16) yk0 = hit ? yprev : yk0; else yk1 = hit ? yprev : yk1; }
;                 }
	v_pk_mul_f32 v[150:151], v[142:143], v[190:191]
	v_pk_fma_f32 v[150:151], v[144:145], v[198:199], v[150:151]
	v_pk_mul_f32 v[152:153], v[142:143], v[236:237]
	v_add_f32_e32 v154, v150, v151
	v_pk_fma_f32 v[152:153], v[144:145], v[238:239], v[152:153]
	v_pk_mul_f32 v[146:147], v[142:143], v[192:193]
	v_add_f32_dpp v154, v154, v154 quad_perm:[1,0,3,2] row_mask:0xf bank_mask:0xf bound_ctrl:1
	v_pk_mul_f32 v[148:149], v[144:145], v[200:201]
	v_add_f32_e32 v167, v152, v153
	v_add_f32_dpp v154, v154, v154 quad_perm:[2,3,0,1] row_mask:0xf bank_mask:0xf bound_ctrl:1
	v_pk_fma_f32 v[146:147], v[240:241], v[196:197], v[146:147] op_sel:[0,0,0] op_sel_hi:[0,1,1]
	v_pk_fma_f32 v[148:149], v[240:241], v[204:205], v[148:149] op_sel:[0,0,0] op_sel_hi:[0,1,1]
	v_add_f32_dpp v154, v154, v154 row_half_mirror row_mask:0xf bank_mask:0xf bound_ctrl:1
	ds_read_b128 v[126:129], v182 offset:21504
	ds_read_b128 v[130:133], v182 offset:21520
	v_add_f32_dpp v154, v154, v154 row_mirror row_mask:0xf bank_mask:0xf bound_ctrl:1
	ds_read_b64 v[236:237], v182 offset:21536
	ds_read_b128 v[134:137], v183 offset:21504
	v_pk_fma_f32 v[146:147], v[154:155], v[194:195], v[146:147] op_sel_hi:[0,1,1]
	v_pk_fma_f32 v[148:149], v[154:155], v[202:203], v[148:149] op_sel_hi:[0,1,1]
	ds_read_b128 v[222:225], v183 offset:21520
	ds_read_b64 v[238:239], v183 offset:21536
	ds_read2_b32 v[242:243], v186 offset0:224 offset1:240
	s_waitcnt lgkmcnt(7)
	v_pk_mul_f32 v[150:151], v[146:147], v[206:207]
	v_pk_fma_f32 v[150:151], v[148:149], v[214:215], v[150:151]
	v_pk_mul_f32 v[152:153], v[146:147], v[228:229]
	v_add_f32_e32 v154, v150, v151
	v_pk_fma_f32 v[152:153], v[148:149], v[230:231], v[152:153]
	v_pk_mul_f32 v[142:143], v[146:147], v[208:209]
	v_add_f32_dpp v154, v154, v154 quad_perm:[1,0,3,2] row_mask:0xf bank_mask:0xf bound_ctrl:1
	v_pk_mul_f32 v[144:145], v[148:149], v[216:217]
	v_add_f32_e32 v168, v152, v153
	v_add_f32_dpp v154, v154, v154 quad_perm:[2,3,0,1] row_mask:0xf bank_mask:0xf bound_ctrl:1
	v_pk_fma_f32 v[142:143], v[240:241], v[212:213], v[142:143] op_sel:[1,0,0] op_sel_hi:[1,1,1]
	v_pk_fma_f32 v[144:145], v[240:241], v[220:221], v[144:145] op_sel:[1,0,0] op_sel_hi:[1,1,1]
	v_add_f32_dpp v154, v154, v154 row_half_mirror row_mask:0xf bank_mask:0xf bound_ctrl:1
	ds_read_b128 v[190:193], v182 offset:23040
	ds_read_b128 v[194:197], v182 offset:23056
	v_add_f32_dpp v154, v154, v154 row_mirror row_mask:0xf bank_mask:0xf bound_ctrl:1
	ds_read_b64 v[228:229], v182 offset:23072
	v_pk_fma_f32 v[142:143], v[154:155], v[210:211], v[142:143] op_sel_hi:[0,1,1]
	v_pk_fma_f32 v[144:145], v[154:155], v[218:219], v[144:145] op_sel_hi:[0,1,1]
	ds_read_b128 v[198:201], v183 offset:23040
	ds_read_b128 v[202:205], v183 offset:23056
	ds_read_b64 v[230:231], v183 offset:23072
	s_waitcnt lgkmcnt(6)
	v_pk_mul_f32 v[150:151], v[142:143], v[126:127]
	v_pk_fma_f32 v[150:151], v[144:145], v[134:135], v[150:151]
	v_pk_mul_f32 v[152:153], v[142:143], v[232:233]
	v_add_f32_e32 v154, v150, v151
	v_pk_fma_f32 v[152:153], v[144:145], v[234:235], v[152:153]
	v_pk_mul_f32 v[146:147], v[142:143], v[128:129]
	v_add_f32_dpp v154, v154, v154 quad_perm:[1,0,3,2] row_mask:0xf bank_mask:0xf bound_ctrl:1
	v_pk_mul_f32 v[148:149], v[144:145], v[136:137]
	v_add_f32_e32 v169, v152, v153
	v_add_f32_dpp v154, v154, v154 quad_perm:[2,3,0,1] row_mask:0xf bank_mask:0xf bound_ctrl:1
	v_pk_fma_f32 v[146:147], v[242:243], v[132:133], v[146:147] op_sel:[0,0,0] op_sel_hi:[0,1,1]
	v_pk_fma_f32 v[148:149], v[242:243], v[224:225], v[148:149] op_sel:[0,0,0] op_sel_hi:[0,1,1]
	v_add_f32_dpp v154, v154, v154 row_half_mirror row_mask:0xf bank_mask:0xf bound_ctrl:1
	ds_read_b128 v[206:209], v182 offset:24576
	ds_read_b128 v[210:213], v182 offset:24592
	v_add_f32_dpp v154, v154, v154 row_mirror row_mask:0xf bank_mask:0xf bound_ctrl:1
	ds_read_b64 v[232:233], v182 offset:24608
	ds_read_b128 v[214:217], v183 offset:24576
	v_pk_fma_f32 v[146:147], v[154:155], v[130:131], v[146:147] op_sel_hi:[0,1,1]
	v_pk_fma_f32 v[148:149], v[154:155], v[222:223], v[148:149] op_sel_hi:[0,1,1]
	ds_read_b128 v[218:221], v183 offset:24592
	ds_read_b64 v[234:235], v183 offset:24608
	ds_read2_b32 v[240:241], v189 offset0:0 offset1:16
	s_waitcnt lgkmcnt(7)
	v_pk_mul_f32 v[150:151], v[146:147], v[190:191]
	v_pk_fma_f32 v[150:151], v[148:149], v[198:199], v[150:151]
	v_pk_mul_f32 v[152:153], v[146:147], v[236:237]
	v_add_f32_e32 v154, v150, v151
	v_pk_fma_f32 v[152:153], v[148:149], v[238:239], v[152:153]
	v_pk_mul_f32 v[142:143], v[146:147], v[192:193]
	v_add_f32_dpp v154, v154, v154 quad_perm:[1,0,3,2] row_mask:0xf bank_mask:0xf bound_ctrl:1
	v_pk_mul_f32 v[144:145], v[148:149], v[200:201]
	v_add_f32_e32 v170, v152, v153
	v_add_f32_dpp v154, v154, v154 quad_perm:[2,3,0,1] row_mask:0xf bank_mask:0xf bound_ctrl:1
	v_pk_fma_f32 v[142:143], v[242:243], v[196:197], v[142:143] op_sel:[1,0,0] op_sel_hi:[1,1,1]
	v_pk_fma_f32 v[144:145], v[242:243], v[204:205], v[144:145] op_sel:[1,0,0] op_sel_hi:[1,1,1]
	v_add_f32_dpp v154, v154, v154 row_half_mirror row_mask:0xf bank_mask:0xf bound_ctrl:1
	ds_read_b128 v[126:129], v182 offset:26112
	ds_read_b128 v[130:133], v182 offset:26128
	v_add_f32_dpp v154, v154, v154 row_mirror row_mask:0xf bank_mask:0xf bound_ctrl:1
	ds_read_b64 v[236:237], v182 offset:26144
	v_pk_fma_f32 v[142:143], v[154:155], v[194:195], v[142:143] op_sel_hi:[0,1,1]
	v_pk_fma_f32 v[144:145], v[154:155], v[202:203], v[144:145] op_sel_hi:[0,1,1]
	ds_read_b128 v[134:137], v183 offset:26112
	ds_read_b128 v[222:225], v183 offset:26128
	ds_read_b64 v[238:239], v183 offset:26144
	s_waitcnt lgkmcnt(6)
; __device__ __forceinline__ void wkv_phase(const WkvT& W, unsigned char* lds) {
;     ...
;                 const float* pp = sP + bo + jj * 12;
;                 const float* pv = sV + bi * 512 + il;
;                 f32x4 nA = *(const f32x4*)pp, nB = *(const f32x4*)(pp + 4); f32x2 nr = *(const f32x2*)(pp + 8); float nv = pv[0];
;                 float yk0 = 0.f, yk1 = 0.f, ep = 0.f;
;                 const bool oddrow = (lane & 16) != 0;
; #pragma unroll
;                 for (int t = 0; t < 32; ++t) {
;                     const f32x2 a2 = {nA[0], nA[1]}, w2 = {nA[2], nA[3]}, b2 = {nB[0], nB[1]}, k2 = {nB[2], nB[3]}, r2 = nr; const float v = nv;
;                     if (t + 1 < 32) { nA = *(const f32x4*)(pp + (t + 1) * 384); nB = *(const f32x4*)(pp + (t + 1) * 384 + 4); nr = *(const f32x2*)(pp + (t + 1) * 384 + 8); nv = pv[(t + 1) * 16]; }
;                     float S0 = S.x, S1 = S.y;
;                     float d = S0 * a2.x; d = __builtin_fmaf(S1, a2.y, d);
;                     float t0 = S0 * w2.x; t0 = __builtin_fmaf(v, k2.x, t0); asm volatile("" : "+v"(t0));
;                     float t1 = S1 * w2.y; t1 = __builtin_fmaf(v, k2.y, t1); asm volatile("" : "+v"(t1));
;                     float yprev; const float sa = wkv_reduce(d, ep, yprev);
;                     S0 = __builtin_fmaf(sa, b2.x, t0); asm volatile("" : "+v"(S0));
;                     S1 = __builtin_fmaf(sa, b2.y, t1); asm volatile("" : "+v"(S1));
;                     ep = S0 * r2.x; ep = __builtin_fmaf(S1, r2.y, ep);
;                     S.x = S0; S.y = S1;
;                     if (t >= 1) { const bool hit = oddrow && ((lane & 15) == ((t - 1) & 15)); if (t <= 16) yk0 = hit ? yprev : yk0; else yk1 = hit ? yprev : yk1; }
;                 }
;                 { float ylast; (void)wkv_reduce(0.f, ep, ylast); yk1 = (oddrow && (lane & 15) == 15) ? ylast : yk1; }
;                 if (oddrow) { sY[bi * 512 + (lane & 15) * 16 + il] = yk0; sY[bi * 512 + (16 + (lane & 15)) * 16 + il] = yk1; }
	v_pk_mul_f32 v[150:151], v[142:143], v[206:207]
	v_pk_fma_f32 v[150:151], v[144:145], v[214:215], v[150:151]
	v_pk_mul_f32 v[152:153], v[142:143], v[228:229]
	v_add_f32_e32 v154, v150, v151
	v_pk_fma_f32 v[152:153], v[144:145], v[230:231], v[152:153]
	v_pk_mul_f32 v[146:147], v[142:143], v[208:209]
	v_add_f32_dpp v154, v154, v154 quad_perm:[1,0,3,2] row_mask:0xf bank_mask:0xf bound_ctrl:1
	v_pk_mul_f32 v[148:149], v[144:145], v[216:217]
	v_add_f32_e32 v171, v152, v153
	v_add_f32_dpp v154, v154, v154 quad_perm:[2,3,0,1] row_mask:0xf bank_mask:0xf bound_ctrl:1
	v_pk_fma_f32 v[146:147], v[240:241], v[212:213], v[146:147] op_sel:[0,0,0] op_sel_hi:[0,1,1]
	v_pk_fma_f32 v[148:149], v[240:241], v[220:221], v[148:149] op_sel:[0,0,0] op_sel_hi:[0,1,1]
	v_add_f32_dpp v154, v154, v154 row_half_mirror row_mask:0xf bank_mask:0xf bound_ctrl:1
	ds_read_b128 v[190:193], v182 offset:27648
	ds_read_b128 v[194:197], v182 offset:27664
	v_add_f32_dpp v154, v154, v154 row_mirror row_mask:0xf bank_mask:0xf bound_ctrl:1
	ds_read_b64 v[228:229], v182 offset:27680
	ds_read_b128 v[198:201], v183 offset:27648
	v_pk_fma_f32 v[146:147], v[154:155], v[210:211], v[146:147] op_sel_hi:[0,1,1]
	v_pk_fma_f32 v[148:149], v[154:155], v[218:219], v[148:149] op_sel_hi:[0,1,1]
	ds_read_b128 v[202:205], v183 offset:27664
	ds_read_b64 v[230:231], v183 offset:27680
	ds_read2_b32 v[242:243], v189 offset0:32 offset1:48
	s_waitcnt lgkmcnt(7)
	v_add_f32_dpp v172, v156, v156 row_ror:8 row_mask:0xf bank_mask:0x3
	v_add_f32_dpp v172, v164, v164 row_ror:8 row_mask:0xf bank_mask:0xc
	v_add_f32_dpp v173, v157, v157 row_ror:8 row_mask:0xf bank_mask:0x3
	v_add_f32_dpp v173, v165, v165 row_ror:8 row_mask:0xf bank_mask:0xc
	v_add_f32_dpp v174, v158, v158 row_ror:8 row_mask:0xf bank_mask:0x3
	v_add_f32_dpp v174, v166, v166 row_ror:8 row_mask:0xf bank_mask:0xc
	v_add_f32_dpp v175, v159, v159 row_ror:8 row_mask:0xf bank_mask:0x3
	v_add_f32_dpp v175, v167, v167 row_ror:8 row_mask:0xf bank_mask:0xc
	v_add_f32_dpp v176, v160, v160 row_ror:8 row_mask:0xf bank_mask:0x3
	v_add_f32_dpp v176, v168, v168 row_ror:8 row_mask:0xf bank_mask:0xc
	v_add_f32_dpp v177, v161, v161 row_ror:8 row_mask:0xf bank_mask:0x3
	v_add_f32_dpp v177, v169, v169 row_ror:8 row_mask:0xf bank_mask:0xc
	v_add_f32_dpp v178, v162, v162 row_ror:8 row_mask:0xf bank_mask:0x3
	v_add_f32_dpp v178, v170, v170 row_ror:8 row_mask:0xf bank_mask:0xc
	v_add_f32_dpp v179, v163, v163 row_ror:8 row_mask:0xf bank_mask:0x3
	v_add_f32_dpp v179, v171, v171 row_ror:8 row_mask:0xf bank_mask:0xc
	v_add_f32_dpp v156, v172, v172 row_half_mirror row_mask:0xf bank_mask:0x5
	v_add_f32_dpp v156, v176, v176 row_half_mirror row_mask:0xf bank_mask:0xa
	v_add_f32_dpp v157, v173, v173 row_half_mirror row_mask:0xf bank_mask:0x5
	v_add_f32_dpp v157, v177, v177 row_half_mirror row_mask:0xf bank_mask:0xa
	v_add_f32_dpp v158, v174, v174 row_half_mirror row_mask:0xf bank_mask:0x5
	v_add_f32_dpp v158, v178, v178 row_half_mirror row_mask:0xf bank_mask:0xa
	v_add_f32_dpp v159, v175, v175 row_half_mirror row_mask:0xf bank_mask:0x5
	v_add_f32_dpp v159, v179, v179 row_half_mirror row_mask:0xf bank_mask:0xa
	v_cndmask_b32_e64 v176, v158, v156, s[14:15]
	v_cndmask_b32_e64 v177, v159, v157, s[14:15]
	v_cndmask_b32_e64 v178, v156, v158, s[14:15]
	v_cndmask_b32_e64 v179, v157, v159, s[14:15]
	v_add_f32_dpp v172, v176, v178 quad_perm:[2,3,0,1] row_mask:0xf bank_mask:0xf
	v_add_f32_dpp v173, v177, v179 quad_perm:[2,3,0,1] row_mask:0xf bank_mask:0xf
	v_cndmask_b32_e64 v176, v173, v172, s[16:17]
	v_cndmask_b32_e64 v178, v172, v173, s[16:17]
	s_nop 0
	v_add_f32_dpp v180, v176, v178 quad_perm:[1,0,3,2] row_mask:0xf bank_mask:0xf
	v_pk_mul_f32 v[150:151], v[146:147], v[126:127]
	v_pk_fma_f32 v[150:151], v[148:149], v[134:135], v[150:151]
	v_pk_mul_f32 v[152:153], v[146:147], v[232:233]
	v_add_f32_e32 v154, v150, v151
	v_pk_fma_f32 v[152:153], v[148:149], v[234:235], v[152:153]
	v_pk_mul_f32 v[142:143], v[146:147], v[128:129]
	v_add_f32_dpp v154, v154, v154 quad_perm:[1,0,3,2] row_mask:0xf bank_mask:0xf bound_ctrl:1
	v_pk_mul_f32 v[144:145], v[148:149], v[136:137]
	v_add_f32_e32 v156, v152, v153
	v_add_f32_dpp v154, v154, v154 quad_perm:[2,3,0,1] row_mask:0xf bank_mask:0xf bound_ctrl:1
	v_pk_fma_f32 v[142:143], v[240:241], v[132:133], v[142:143] op_sel:[1,0,0] op_sel_hi:[1,1,1]
	v_pk_fma_f32 v[144:145], v[240:241], v[224:225], v[144:145] op_sel:[1,0,0] op_sel_hi:[1,1,1]
	v_add_f32_dpp v154, v154, v154 row_half_mirror row_mask:0xf bank_mask:0xf bound_ctrl:1
	ds_read_b128 v[206:209], v182 offset:29184
	ds_read_b128 v[210:213], v182 offset:29200
	v_add_f32_dpp v154, v154, v154 row_mirror row_mask:0xf bank_mask:0xf bound_ctrl:1
	ds_read_b64 v[232:233], v182 offset:29216
	v_pk_fma_f32 v[142:143], v[154:155], v[130:131], v[142:143] op_sel_hi:[0,1,1]
	v_pk_fma_f32 v[144:145], v[154:155], v[222:223], v[144:145] op_sel_hi:[0,1,1]
	ds_read_b128 v[214:217], v183 offset:29184
	ds_read_b128 v[218:221], v183 offset:29200
	ds_read_b64 v[234:235], v183 offset:29216
	s_waitcnt lgkmcnt(6)
; __device__ __forceinline__ void wkv_phase(const WkvT& W, unsigned char* lds) {
;     ...
;                 const float* pp = sP + bo + jj * 12;
;                 const float* pv = sV + bi * 512 + il;
;                 f32x4 nA = *(const f32x4*)pp, nB = *(const f32x4*)(pp + 4); f32x2 nr = *(const f32x2*)(pp + 8); float nv = pv[0];
;                 float yk0 = 0.f, yk1 = 0.f, ep = 0.f;
;                 const bool oddrow = (lane & 16) != 0;
; #pragma unroll
;                 for (int t = 0; t < 32; ++t) {
;                     const f32x2 a2 = {nA[0], nA[1]}, w2 = {nA[2], nA[3]}, b2 = {nB[0], nB[1]}, k2 = {nB[2], nB[3]}, r2 = nr; const float v = nv;
;                     if (t + 1 < 32) { nA = *(const f32x4*)(pp + (t + 1) * 384); nB = *(const f32x4*)(pp + (t + 1) * 384 + 4); nr = *(const f32x2*)(pp + (t + 1) * 384 + 8); nv = pv[(t + 1) * 16]; }
;                     float S0 = S.x, S1 = S.y;
;                     float d = S0 * a2.x; d = __builtin_fmaf(S1, a2.y, d);
;                     float t0 = S0 * w2.x; t0 = __builtin_fmaf(v, k2.x, t0); asm volatile("" : "+v"(t0));
;                     float t1 = S1 * w2.y; t1 = __builtin_fmaf(v, k2.y, t1); asm volatile("" : "+v"(t1));
;                     float yprev; const float sa = wkv_reduce(d, ep, yprev);
;                     S0 = __builtin_fmaf(sa, b2.x, t0); asm volatile("" : "+v"(S0));
;                     S1 = __builtin_fmaf(sa, b2.y, t1); asm volatile("" : "+v"(S1));
;                     ep = S0 * r2.x; ep = __builtin_fmaf(S1, r2.y, ep);
;                     S.x = S0; S.y = S1;
;                     if (t >= 1) { const bool hit = oddrow && ((lane & 15) == ((t - 1) & 15)); if (t <= 16) yk0 = hit ? yprev : yk0; else yk1 = hit ? yprev : yk1; }
;                 }
	v_pk_mul_f32 v[150:151], v[142:143], v[190:191]
	v_pk_fma_f32 v[150:151], v[144:145], v[198:199], v[150:151]
	v_pk_mul_f32 v[152:153], v[142:143], v[236:237]
	v_add_f32_e32 v154, v150, v151
	v_pk_fma_f32 v[152:153], v[144:145], v[238:239], v[152:153]
	v_pk_mul_f32 v[146:147], v[142:143], v[192:193]
	v_add_f32_dpp v154, v154, v154 quad_perm:[1,0,3,2] row_mask:0xf bank_mask:0xf bound_ctrl:1
	v_pk_mul_f32 v[148:149], v[144:145], v[200:201]
	v_add_f32_e32 v157, v152, v153
	v_add_f32_dpp v154, v154, v154 quad_perm:[2,3,0,1] row_mask:0xf bank_mask:0xf bound_ctrl:1
	v_pk_fma_f32 v[146:147], v[242:243], v[196:197], v[146:147] op_sel:[0,0,0] op_sel_hi:[0,1,1]
	v_pk_fma_f32 v[148:149], v[242:243], v[204:205], v[148:149] op_sel:[0,0,0] op_sel_hi:[0,1,1]
	v_add_f32_dpp v154, v154, v154 row_half_mirror row_mask:0xf bank_mask:0xf bound_ctrl:1
	ds_read_b128 v[126:129], v182 offset:30720
	ds_read_b128 v[130:133], v182 offset:30736
	v_add_f32_dpp v154, v154, v154 row_mirror row_mask:0xf bank_mask:0xf bound_ctrl:1
	ds_read_b64 v[236:237], v182 offset:30752
	ds_read_b128 v[134:137], v183 offset:30720
	v_pk_fma_f32 v[146:147], v[154:155], v[194:195], v[146:147] op_sel_hi:[0,1,1]
	v_pk_fma_f32 v[148:149], v[154:155], v[202:203], v[148:149] op_sel_hi:[0,1,1]
	ds_read_b128 v[222:225], v183 offset:30736
	ds_read_b64 v[238:239], v183 offset:30752
	ds_read2_b32 v[240:241], v189 offset0:64 offset1:80
	s_waitcnt lgkmcnt(7)
	v_pk_mul_f32 v[150:151], v[146:147], v[206:207]
	v_pk_fma_f32 v[150:151], v[148:149], v[214:215], v[150:151]
	v_pk_mul_f32 v[152:153], v[146:147], v[228:229]
	v_add_f32_e32 v154, v150, v151
	v_pk_fma_f32 v[152:153], v[148:149], v[230:231], v[152:153]
	v_pk_mul_f32 v[142:143], v[146:147], v[208:209]
	v_add_f32_dpp v154, v154, v154 quad_perm:[1,0,3,2] row_mask:0xf bank_mask:0xf bound_ctrl:1
	v_pk_mul_f32 v[144:145], v[148:149], v[216:217]
	v_add_f32_e32 v158, v152, v153
	v_add_f32_dpp v154, v154, v154 quad_perm:[2,3,0,1] row_mask:0xf bank_mask:0xf bound_ctrl:1
	v_pk_fma_f32 v[142:143], v[242:243], v[212:213], v[142:143] op_sel:[1,0,0] op_sel_hi:[1,1,1]
	v_pk_fma_f32 v[144:145], v[242:243], v[220:221], v[144:145] op_sel:[1,0,0] op_sel_hi:[1,1,1]
	v_add_f32_dpp v154, v154, v154 row_half_mirror row_mask:0xf bank_mask:0xf bound_ctrl:1
	ds_read_b128 v[190:193], v182 offset:32256
	ds_read_b128 v[194:197], v182 offset:32272
	v_add_f32_dpp v154, v154, v154 row_mirror row_mask:0xf bank_mask:0xf bound_ctrl:1
	ds_read_b64 v[228:229], v182 offset:32288
	v_pk_fma_f32 v[142:143], v[154:155], v[210:211], v[142:143] op_sel_hi:[0,1,1]
	v_pk_fma_f32 v[144:145], v[154:155], v[218:219], v[144:145] op_sel_hi:[0,1,1]
	ds_read_b128 v[198:201], v183 offset:32256
	ds_read_b128 v[202:205], v183 offset:32272
	ds_read_b64 v[230:231], v183 offset:32288
	s_waitcnt lgkmcnt(6)
	v_pk_mul_f32 v[150:151], v[142:143], v[126:127]
	v_pk_fma_f32 v[150:151], v[144:145], v[134:135], v[150:151]
	v_pk_mul_f32 v[152:153], v[142:143], v[232:233]
	v_add_f32_e32 v154, v150, v151
	v_pk_fma_f32 v[152:153], v[144:145], v[234:235], v[152:153]
	v_pk_mul_f32 v[146:147], v[142:143], v[128:129]
	v_add_f32_dpp v154, v154, v154 quad_perm:[1,0,3,2] row_mask:0xf bank_mask:0xf bound_ctrl:1
	v_pk_mul_f32 v[148:149], v[144:145], v[136:137]
	v_add_f32_e32 v159, v152, v153
	v_add_f32_dpp v154, v154, v154 quad_perm:[2,3,0,1] row_mask:0xf bank_mask:0xf bound_ctrl:1
	v_pk_fma_f32 v[146:147], v[240:241], v[132:133], v[146:147] op_sel:[0,0,0] op_sel_hi:[0,1,1]
	v_pk_fma_f32 v[148:149], v[240:241], v[224:225], v[148:149] op_sel:[0,0,0] op_sel_hi:[0,1,1]
	v_add_f32_dpp v154, v154, v154 row_half_mirror row_mask:0xf bank_mask:0xf bound_ctrl:1
	ds_read_b128 v[206:209], v182 offset:33792
	ds_read_b128 v[210:213], v182 offset:33808
	v_add_f32_dpp v154, v154, v154 row_mirror row_mask:0xf bank_mask:0xf bound_ctrl:1
	ds_read_b64 v[232:233], v182 offset:33824
	ds_read_b128 v[214:217], v183 offset:33792
	v_pk_fma_f32 v[146:147], v[154:155], v[130:131], v[146:147] op_sel_hi:[0,1,1]
	v_pk_fma_f32 v[148:149], v[154:155], v[222:223], v[148:149] op_sel_hi:[0,1,1]
	ds_read_b128 v[218:221], v183 offset:33808
	ds_read_b64 v[234:235], v183 offset:33824
	ds_read2_b32 v[242:243], v189 offset0:96 offset1:112
	s_waitcnt lgkmcnt(7)
	v_pk_mul_f32 v[150:151], v[146:147], v[190:191]
	v_pk_fma_f32 v[150:151], v[148:149], v[198:199], v[150:151]
	v_pk_mul_f32 v[152:153], v[146:147], v[236:237]
	v_add_f32_e32 v154, v150, v151
	v_pk_fma_f32 v[152:153], v[148:149], v[238:239], v[152:153]
	v_pk_mul_f32 v[142:143], v[146:147], v[192:193]
	v_add_f32_dpp v154, v154, v154 quad_perm:[1,0,3,2] row_mask:0xf bank_mask:0xf bound_ctrl:1
	v_pk_mul_f32 v[144:145], v[148:149], v[200:201]
	v_add_f32_e32 v160, v152, v153
	v_add_f32_dpp v154, v154, v154 quad_perm:[2,3,0,1] row_mask:0xf bank_mask:0xf bound_ctrl:1
	v_pk_fma_f32 v[142:143], v[240:241], v[196:197], v[142:143] op_sel:[1,0,0] op_sel_hi:[1,1,1]
	v_pk_fma_f32 v[144:145], v[240:241], v[204:205], v[144:145] op_sel:[1,0,0] op_sel_hi:[1,1,1]
	v_add_f32_dpp v154, v154, v154 row_half_mirror row_mask:0xf bank_mask:0xf bound_ctrl:1
	ds_read_b128 v[126:129], v182 offset:35328
	ds_read_b128 v[130:133], v182 offset:35344
	v_add_f32_dpp v154, v154, v154 row_mirror row_mask:0xf bank_mask:0xf bound_ctrl:1
	ds_read_b64 v[236:237], v182 offset:35360
	v_pk_fma_f32 v[142:143], v[154:155], v[194:195], v[142:143] op_sel_hi:[0,1,1]
	v_pk_fma_f32 v[144:145], v[154:155], v[202:203], v[144:145] op_sel_hi:[0,1,1]
	ds_read_b128 v[134:137], v183 offset:35328
	ds_read_b128 v[222:225], v183 offset:35344
	ds_read_b64 v[238:239], v183 offset:35360
	s_waitcnt lgkmcnt(6)
; __device__ __forceinline__ void wkv_phase(const WkvT& W, unsigned char* lds) {
;     ...
;                 const float* pp = sP + bo + jj * 12;
;                 const float* pv = sV + bi * 512 + il;
;                 f32x4 nA = *(const f32x4*)pp, nB = *(const f32x4*)(pp + 4); f32x2 nr = *(const f32x2*)(pp + 8); float nv = pv[0];
;                 float yk0 = 0.f, yk1 = 0.f, ep = 0.f;
;                 const bool oddrow = (lane & 16) != 0;
; #pragma unroll
;                 for (int t = 0; t < 32; ++t) {
;                     const f32x2 a2 = {nA[0], nA[1]}, w2 = {nA[2], nA[3]}, b2 = {nB[0], nB[1]}, k2 = {nB[2], nB[3]}, r2 = nr; const float v = nv;
;                     if (t + 1 < 32) { nA = *(const f32x4*)(pp + (t + 1) * 384); nB = *(const f32x4*)(pp + (t + 1) * 384 + 4); nr = *(const f32x2*)(pp + (t + 1) * 384 + 8); nv = pv[(t + 1) * 16]; }
;                     float S0 = S.x, S1 = S.y;
;                     float d = S0 * a2.x; d = __builtin_fmaf(S1, a2.y, d);
;                     float t0 = S0 * w2.x; t0 = __builtin_fmaf(v, k2.x, t0); asm volatile("" : "+v"(t0));
;                     float t1 = S1 * w2.y; t1 = __builtin_fmaf(v, k2.y, t1); asm volatile("" : "+v"(t1));
;                     float yprev; const float sa = wkv_reduce(d, ep, yprev);
;                     S0 = __builtin_fmaf(sa, b2.x, t0); asm volatile("" : "+v"(S0));
;                     S1 = __builtin_fmaf(sa, b2.y, t1); asm volatile("" : "+v"(S1));
;                     ep = S0 * r2.x; ep = __builtin_fmaf(S1, r2.y, ep);
;                     S.x = S0; S.y = S1;
;                     if (t >= 1) { const bool hit = oddrow && ((lane & 15) == ((t - 1) & 15)); if (t <= 16) yk0 = hit ? yprev : yk0; else yk1 = hit ? yprev : yk1; }
;                 }
	v_pk_mul_f32 v[150:151], v[142:143], v[206:207]
	v_pk_fma_f32 v[150:151], v[144:145], v[214:215], v[150:151]
	v_pk_mul_f32 v[152:153], v[142:143], v[228:229]
	v_add_f32_e32 v154, v150, v151
	v_pk_fma_f32 v[152:153], v[144:145], v[230:231], v[152:153]
	v_pk_mul_f32 v[146:147], v[142:143], v[208:209]
	v_add_f32_dpp v154, v154, v154 quad_perm:[1,0,3,2] row_mask:0xf bank_mask:0xf bound_ctrl:1
	v_pk_mul_f32 v[148:149], v[144:145], v[216:217]
	v_add_f32_e32 v161, v152, v153
	v_add_f32_dpp v154, v154, v154 quad_perm:[2,3,0,1] row_mask:0xf bank_mask:0xf bound_ctrl:1
	v_pk_fma_f32 v[146:147], v[242:243], v[212:213], v[146:147] op_sel:[0,0,0] op_sel_hi:[0,1,1]
	v_pk_fma_f32 v[148:149], v[242:243], v[220:221], v[148:149] op_sel:[0,0,0] op_sel_hi:[0,1,1]
	v_add_f32_dpp v154, v154, v154 row_half_mirror row_mask:0xf bank_mask:0xf bound_ctrl:1
	ds_read_b128 v[190:193], v182 offset:36864
	ds_read_b128 v[194:197], v182 offset:36880
	v_add_f32_dpp v154, v154, v154 row_mirror row_mask:0xf bank_mask:0xf bound_ctrl:1
	ds_read_b64 v[228:229], v182 offset:36896
	ds_read_b128 v[198:201], v183 offset:36864
	v_pk_fma_f32 v[146:147], v[154:155], v[210:211], v[146:147] op_sel_hi:[0,1,1]
	v_pk_fma_f32 v[148:149], v[154:155], v[218:219], v[148:149] op_sel_hi:[0,1,1]
	ds_read_b128 v[202:205], v183 offset:36880
	ds_read_b64 v[230:231], v183 offset:36896
	ds_read2_b32 v[240:241], v189 offset0:128 offset1:144
	s_waitcnt lgkmcnt(7)
	v_pk_mul_f32 v[150:151], v[146:147], v[126:127]
	v_pk_fma_f32 v[150:151], v[148:149], v[134:135], v[150:151]
	v_pk_mul_f32 v[152:153], v[146:147], v[232:233]
	v_add_f32_e32 v154, v150, v151
	v_pk_fma_f32 v[152:153], v[148:149], v[234:235], v[152:153]
	v_pk_mul_f32 v[142:143], v[146:147], v[128:129]
	v_add_f32_dpp v154, v154, v154 quad_perm:[1,0,3,2] row_mask:0xf bank_mask:0xf bound_ctrl:1
	v_pk_mul_f32 v[144:145], v[148:149], v[136:137]
	v_add_f32_e32 v162, v152, v153
	v_add_f32_dpp v154, v154, v154 quad_perm:[2,3,0,1] row_mask:0xf bank_mask:0xf bound_ctrl:1
	v_pk_fma_f32 v[142:143], v[242:243], v[132:133], v[142:143] op_sel:[1,0,0] op_sel_hi:[1,1,1]
	v_pk_fma_f32 v[144:145], v[242:243], v[224:225], v[144:145] op_sel:[1,0,0] op_sel_hi:[1,1,1]
	v_add_f32_dpp v154, v154, v154 row_half_mirror row_mask:0xf bank_mask:0xf bound_ctrl:1
	ds_read_b128 v[206:209], v182 offset:38400
	ds_read_b128 v[210:213], v182 offset:38416
	v_add_f32_dpp v154, v154, v154 row_mirror row_mask:0xf bank_mask:0xf bound_ctrl:1
	ds_read_b64 v[232:233], v182 offset:38432
	v_pk_fma_f32 v[142:143], v[154:155], v[130:131], v[142:143] op_sel_hi:[0,1,1]
	v_pk_fma_f32 v[144:145], v[154:155], v[222:223], v[144:145] op_sel_hi:[0,1,1]
	ds_read_b128 v[214:217], v183 offset:38400
	ds_read_b128 v[218:221], v183 offset:38416
	ds_read_b64 v[234:235], v183 offset:38432
	s_waitcnt lgkmcnt(6)
	v_pk_mul_f32 v[150:151], v[142:143], v[190:191]
	v_pk_fma_f32 v[150:151], v[144:145], v[198:199], v[150:151]
	v_pk_mul_f32 v[152:153], v[142:143], v[236:237]
	v_add_f32_e32 v154, v150, v151
	v_pk_fma_f32 v[152:153], v[144:145], v[238:239], v[152:153]
	v_pk_mul_f32 v[146:147], v[142:143], v[192:193]
	v_add_f32_dpp v154, v154, v154 quad_perm:[1,0,3,2] row_mask:0xf bank_mask:0xf bound_ctrl:1
	v_pk_mul_f32 v[148:149], v[144:145], v[200:201]
	v_add_f32_e32 v163, v152, v153
	v_add_f32_dpp v154, v154, v154 quad_perm:[2,3,0,1] row_mask:0xf bank_mask:0xf bound_ctrl:1
	v_pk_fma_f32 v[146:147], v[240:241], v[196:197], v[146:147] op_sel:[0,0,0] op_sel_hi:[0,1,1]
	v_pk_fma_f32 v[148:149], v[240:241], v[204:205], v[148:149] op_sel:[0,0,0] op_sel_hi:[0,1,1]
	v_add_f32_dpp v154, v154, v154 row_half_mirror row_mask:0xf bank_mask:0xf bound_ctrl:1
	ds_read_b128 v[126:129], v182 offset:39936
	ds_read_b128 v[130:133], v182 offset:39952
	v_add_f32_dpp v154, v154, v154 row_mirror row_mask:0xf bank_mask:0xf bound_ctrl:1
	ds_read_b64 v[236:237], v182 offset:39968
	ds_read_b128 v[134:137], v183 offset:39936
	v_pk_fma_f32 v[146:147], v[154:155], v[194:195], v[146:147] op_sel_hi:[0,1,1]
	v_pk_fma_f32 v[148:149], v[154:155], v[202:203], v[148:149] op_sel_hi:[0,1,1]
	ds_read_b128 v[222:225], v183 offset:39952
	ds_read_b64 v[238:239], v183 offset:39968
	ds_read2_b32 v[242:243], v189 offset0:160 offset1:176
	s_waitcnt lgkmcnt(7)
	v_pk_mul_f32 v[150:151], v[146:147], v[206:207]
	v_pk_fma_f32 v[150:151], v[148:149], v[214:215], v[150:151]
	v_pk_mul_f32 v[152:153], v[146:147], v[228:229]
	v_add_f32_e32 v154, v150, v151
	v_pk_fma_f32 v[152:153], v[148:149], v[230:231], v[152:153]
	v_pk_mul_f32 v[142:143], v[146:147], v[208:209]
	v_add_f32_dpp v154, v154, v154 quad_perm:[1,0,3,2] row_mask:0xf bank_mask:0xf bound_ctrl:1
	v_pk_mul_f32 v[144:145], v[148:149], v[216:217]
	v_add_f32_e32 v164, v152, v153
	v_add_f32_dpp v154, v154, v154 quad_perm:[2,3,0,1] row_mask:0xf bank_mask:0xf bound_ctrl:1
	v_pk_fma_f32 v[142:143], v[240:241], v[212:213], v[142:143] op_sel:[1,0,0] op_sel_hi:[1,1,1]
	v_pk_fma_f32 v[144:145], v[240:241], v[220:221], v[144:145] op_sel:[1,0,0] op_sel_hi:[1,1,1]
	v_add_f32_dpp v154, v154, v154 row_half_mirror row_mask:0xf bank_mask:0xf bound_ctrl:1
	ds_read_b128 v[190:193], v182 offset:41472
	ds_read_b128 v[194:197], v182 offset:41488
	v_add_f32_dpp v154, v154, v154 row_mirror row_mask:0xf bank_mask:0xf bound_ctrl:1
	ds_read_b64 v[228:229], v182 offset:41504
	v_pk_fma_f32 v[142:143], v[154:155], v[210:211], v[142:143] op_sel_hi:[0,1,1]
	v_pk_fma_f32 v[144:145], v[154:155], v[218:219], v[144:145] op_sel_hi:[0,1,1]
	ds_read_b128 v[198:201], v183 offset:41472
	ds_read_b128 v[202:205], v183 offset:41488
	ds_read_b64 v[230:231], v183 offset:41504
	s_waitcnt lgkmcnt(6)
; __device__ __forceinline__ void wkv_phase(const WkvT& W, unsigned char* lds) {
;     ...
;                 const float* pp = sP + bo + jj * 12;
;                 const float* pv = sV + bi * 512 + il;
;                 f32x4 nA = *(const f32x4*)pp, nB = *(const f32x4*)(pp + 4); f32x2 nr = *(const f32x2*)(pp + 8); float nv = pv[0];
;                 float yk0 = 0.f, yk1 = 0.f, ep = 0.f;
;                 const bool oddrow = (lane & 16) != 0;
; #pragma unroll
;                 for (int t = 0; t < 32; ++t) {
;                     const f32x2 a2 = {nA[0], nA[1]}, w2 = {nA[2], nA[3]}, b2 = {nB[0], nB[1]}, k2 = {nB[2], nB[3]}, r2 = nr; const float v = nv;
;                     if (t + 1 < 32) { nA = *(const f32x4*)(pp + (t + 1) * 384); nB = *(const f32x4*)(pp + (t + 1) * 384 + 4); nr = *(const f32x2*)(pp + (t + 1) * 384 + 8); nv = pv[(t + 1) * 16]; }
;                     float S0 = S.x, S1 = S.y;
;                     float d = S0 * a2.x; d = __builtin_fmaf(S1, a2.y, d);
;                     float t0 = S0 * w2.x; t0 = __builtin_fmaf(v, k2.x, t0); asm volatile("" : "+v"(t0));
;                     float t1 = S1 * w2.y; t1 = __builtin_fmaf(v, k2.y, t1); asm volatile("" : "+v"(t1));
;                     float yprev; const float sa = wkv_reduce(d, ep, yprev);
;                     S0 = __builtin_fmaf(sa, b2.x, t0); asm volatile("" : "+v"(S0));
;                     S1 = __builtin_fmaf(sa, b2.y, t1); asm volatile("" : "+v"(S1));
;                     ep = S0 * r2.x; ep = __builtin_fmaf(S1, r2.y, ep);
;                     S.x = S0; S.y = S1;
	v_pk_mul_f32 v[150:151], v[142:143], v[126:127]
	v_pk_fma_f32 v[150:151], v[144:145], v[134:135], v[150:151]
	v_pk_mul_f32 v[152:153], v[142:143], v[232:233]
	v_add_f32_e32 v154, v150, v151
	v_pk_fma_f32 v[152:153], v[144:145], v[234:235], v[152:153]
	v_pk_mul_f32 v[146:147], v[142:143], v[128:129]
	v_add_f32_dpp v154, v154, v154 quad_perm:[1,0,3,2] row_mask:0xf bank_mask:0xf bound_ctrl:1
	v_pk_mul_f32 v[148:149], v[144:145], v[136:137]
	v_add_f32_e32 v165, v152, v153
	v_add_f32_dpp v154, v154, v154 quad_perm:[2,3,0,1] row_mask:0xf bank_mask:0xf bound_ctrl:1
	v_pk_fma_f32 v[146:147], v[242:243], v[132:133], v[146:147] op_sel:[0,0,0] op_sel_hi:[0,1,1]
	v_pk_fma_f32 v[148:149], v[242:243], v[224:225], v[148:149] op_sel:[0,0,0] op_sel_hi:[0,1,1]
	v_add_f32_dpp v154, v154, v154 row_half_mirror row_mask:0xf bank_mask:0xf bound_ctrl:1
	ds_read_b128 v[206:209], v182 offset:43008
	ds_read_b128 v[210:213], v182 offset:43024
	v_add_f32_dpp v154, v154, v154 row_mirror row_mask:0xf bank_mask:0xf bound_ctrl:1
	ds_read_b64 v[232:233], v182 offset:43040
	ds_read_b128 v[214:217], v183 offset:43008
	v_pk_fma_f32 v[146:147], v[154:155], v[130:131], v[146:147] op_sel_hi:[0,1,1]
	v_pk_fma_f32 v[148:149], v[154:155], v[222:223], v[148:149] op_sel_hi:[0,1,1]
	ds_read_b128 v[218:221], v183 offset:43024
	ds_read_b64 v[234:235], v183 offset:43040
	ds_read2_b32 v[240:241], v189 offset0:192 offset1:208
	s_waitcnt lgkmcnt(7)
	v_pk_mul_f32 v[150:151], v[146:147], v[190:191]
	v_pk_fma_f32 v[150:151], v[148:149], v[198:199], v[150:151]
	v_pk_mul_f32 v[152:153], v[146:147], v[236:237]
	v_add_f32_e32 v154, v150, v151
	v_pk_fma_f32 v[152:153], v[148:149], v[238:239], v[152:153]
	v_pk_mul_f32 v[142:143], v[146:147], v[192:193]
	v_add_f32_dpp v154, v154, v154 quad_perm:[1,0,3,2] row_mask:0xf bank_mask:0xf bound_ctrl:1
	v_pk_mul_f32 v[144:145], v[148:149], v[200:201]
	v_add_f32_e32 v166, v152, v153
	v_add_f32_dpp v154, v154, v154 quad_perm:[2,3,0,1] row_mask:0xf bank_mask:0xf bound_ctrl:1
	v_pk_fma_f32 v[142:143], v[242:243], v[196:197], v[142:143] op_sel:[1,0,0] op_sel_hi:[1,1,1]
	v_pk_fma_f32 v[144:145], v[242:243], v[204:205], v[144:145] op_sel:[1,0,0] op_sel_hi:[1,1,1]
	v_add_f32_dpp v154, v154, v154 row_half_mirror row_mask:0xf bank_mask:0xf bound_ctrl:1
	ds_read_b128 v[126:129], v182 offset:44544
	ds_read_b128 v[130:133], v182 offset:44560
	v_add_f32_dpp v154, v154, v154 row_mirror row_mask:0xf bank_mask:0xf bound_ctrl:1
	ds_read_b64 v[236:237], v182 offset:44576
	v_pk_fma_f32 v[142:143], v[154:155], v[194:195], v[142:143] op_sel_hi:[0,1,1]
	v_pk_fma_f32 v[144:145], v[154:155], v[202:203], v[144:145] op_sel_hi:[0,1,1]
	ds_read_b128 v[134:137], v183 offset:44544
	ds_read_b128 v[222:225], v183 offset:44560
	ds_read_b64 v[238:239], v183 offset:44576
	s_waitcnt lgkmcnt(6)
	v_pk_mul_f32 v[150:151], v[142:143], v[206:207]
	v_pk_fma_f32 v[150:151], v[144:145], v[214:215], v[150:151]
	v_pk_mul_f32 v[152:153], v[142:143], v[228:229]
	v_add_f32_e32 v154, v150, v151
	v_pk_fma_f32 v[152:153], v[144:145], v[230:231], v[152:153]
	v_pk_mul_f32 v[146:147], v[142:143], v[208:209]
	v_add_f32_dpp v154, v154, v154 quad_perm:[1,0,3,2] row_mask:0xf bank_mask:0xf bound_ctrl:1
	v_pk_mul_f32 v[148:149], v[144:145], v[216:217]
	v_add_f32_e32 v167, v152, v153
	v_add_f32_dpp v154, v154, v154 quad_perm:[2,3,0,1] row_mask:0xf bank_mask:0xf bound_ctrl:1
	v_pk_fma_f32 v[146:147], v[240:241], v[212:213], v[146:147] op_sel:[0,0,0] op_sel_hi:[0,1,1]
	v_pk_fma_f32 v[148:149], v[240:241], v[220:221], v[148:149] op_sel:[0,0,0] op_sel_hi:[0,1,1]
	v_add_f32_dpp v154, v154, v154 row_half_mirror row_mask:0xf bank_mask:0xf bound_ctrl:1
	ds_read_b128 v[190:193], v182 offset:46080
	ds_read_b128 v[194:197], v182 offset:46096
	v_add_f32_dpp v154, v154, v154 row_mirror row_mask:0xf bank_mask:0xf bound_ctrl:1
	ds_read_b64 v[228:229], v182 offset:46112
	ds_read_b128 v[198:201], v183 offset:46080
	v_pk_fma_f32 v[146:147], v[154:155], v[210:211], v[146:147] op_sel_hi:[0,1,1]
	v_pk_fma_f32 v[148:149], v[154:155], v[218:219], v[148:149] op_sel_hi:[0,1,1]
	ds_read_b128 v[202:205], v183 offset:46096
	ds_read_b64 v[230:231], v183 offset:46112
	ds_read2_b32 v[242:243], v189 offset0:224 offset1:240
	s_waitcnt lgkmcnt(7)
	v_pk_mul_f32 v[150:151], v[146:147], v[126:127]
	v_pk_fma_f32 v[150:151], v[148:149], v[134:135], v[150:151]
	v_pk_mul_f32 v[152:153], v[146:147], v[232:233]
	v_add_f32_e32 v154, v150, v151
	v_pk_fma_f32 v[152:153], v[148:149], v[234:235], v[152:153]
	v_pk_mul_f32 v[142:143], v[146:147], v[128:129]
	v_add_f32_dpp v154, v154, v154 quad_perm:[1,0,3,2] row_mask:0xf bank_mask:0xf bound_ctrl:1
	v_pk_mul_f32 v[144:145], v[148:149], v[136:137]
	v_add_f32_e32 v168, v152, v153
	v_add_f32_dpp v154, v154, v154 quad_perm:[2,3,0,1] row_mask:0xf bank_mask:0xf bound_ctrl:1
	v_pk_fma_f32 v[142:143], v[240:241], v[132:133], v[142:143] op_sel:[1,0,0] op_sel_hi:[1,1,1]
	v_pk_fma_f32 v[144:145], v[240:241], v[224:225], v[144:145] op_sel:[1,0,0] op_sel_hi:[1,1,1]
	v_add_f32_dpp v154, v154, v154 row_half_mirror row_mask:0xf bank_mask:0xf bound_ctrl:1
	ds_read_b128 v[206:209], v182 offset:47616
	ds_read_b128 v[210:213], v182 offset:47632
	v_add_f32_dpp v154, v154, v154 row_mirror row_mask:0xf bank_mask:0xf bound_ctrl:1
	ds_read_b64 v[232:233], v182 offset:47648
	v_pk_fma_f32 v[142:143], v[154:155], v[130:131], v[142:143] op_sel_hi:[0,1,1]
	v_pk_fma_f32 v[144:145], v[154:155], v[222:223], v[144:145] op_sel_hi:[0,1,1]
	ds_read_b128 v[214:217], v183 offset:47616
	ds_read_b128 v[218:221], v183 offset:47632
	ds_read_b64 v[234:235], v183 offset:47648
	s_waitcnt lgkmcnt(6)
; __device__ __forceinline__ void wkv_phase(const WkvT& W, unsigned char* lds) {
;     ...
;                 const float* pp = sP + bo + jj * 12;
;                 const float* pv = sV + bi * 512 + il;
;                 f32x4 nA = *(const f32x4*)pp, nB = *(const f32x4*)(pp + 4); f32x2 nr = *(const f32x2*)(pp + 8); float nv = pv[0];
;                 float yk0 = 0.f, yk1 = 0.f, ep = 0.f;
;                 const bool oddrow = (lane & 16) != 0;
; #pragma unroll
;                 for (int t = 0; t < 32; ++t) {
;                     const f32x2 a2 = {nA[0], nA[1]}, w2 = {nA[2], nA[3]}, b2 = {nB[0], nB[1]}, k2 = {nB[2], nB[3]}, r2 = nr; const float v = nv;
;                     if (t + 1 < 32) { nA = *(const f32x4*)(pp + (t + 1) * 384); nB = *(const f32x4*)(pp + (t + 1) * 384 + 4); nr = *(const f32x2*)(pp + (t + 1) * 384 + 8); nv = pv[(t + 1) * 16]; }
;                     float S0 = S.x, S1 = S.y;
;                     float d = S0 * a2.x; d = __builtin_fmaf(S1, a2.y, d);
;                     float t0 = S0 * w2.x; t0 = __builtin_fmaf(v, k2.x, t0); asm volatile("" : "+v"(t0));
;                     float t1 = S1 * w2.y; t1 = __builtin_fmaf(v, k2.y, t1); asm volatile("" : "+v"(t1));
;                     float yprev; const float sa = wkv_reduce(d, ep, yprev);
;                     S0 = __builtin_fmaf(sa, b2.x, t0); asm volatile("" : "+v"(S0));
;                     S1 = __builtin_fmaf(sa, b2.y, t1); asm volatile("" : "+v"(S1));
;                     ep = S0 * r2.x; ep = __builtin_fmaf(S1, r2.y, ep);
;                     S.x = S0; S.y = S1;
;                     if (t >= 1) { const bool hit = oddrow && ((lane & 15) == ((t - 1) & 15)); if (t <= 16) yk0 = hit ? yprev : yk0; else yk1 = hit ? yprev : yk1; }
;                 }
;                 { float ylast; (void)wkv_reduce(0.f, ep, ylast); yk1 = (oddrow && (lane & 15) == 15) ? ylast : yk1; }
;                 if (oddrow) { sY[bi * 512 + (lane & 15) * 16 + il] = yk0; sY[bi * 512 + (16 + (lane & 15)) * 16 + il] = yk1; }
	v_pk_mul_f32 v[150:151], v[142:143], v[190:191]
	v_pk_fma_f32 v[150:151], v[144:145], v[198:199], v[150:151]
	v_pk_mul_f32 v[152:153], v[142:143], v[236:237]
	v_add_f32_e32 v154, v150, v151
	v_pk_fma_f32 v[152:153], v[144:145], v[238:239], v[152:153]
	v_pk_mul_f32 v[146:147], v[142:143], v[192:193]
	v_add_f32_dpp v154, v154, v154 quad_perm:[1,0,3,2] row_mask:0xf bank_mask:0xf bound_ctrl:1
	v_pk_mul_f32 v[148:149], v[144:145], v[200:201]
	v_add_f32_e32 v169, v152, v153
	v_add_f32_dpp v154, v154, v154 quad_perm:[2,3,0,1] row_mask:0xf bank_mask:0xf bound_ctrl:1
	v_pk_fma_f32 v[146:147], v[242:243], v[196:197], v[146:147] op_sel:[0,0,0] op_sel_hi:[0,1,1]
	v_pk_fma_f32 v[148:149], v[242:243], v[204:205], v[148:149] op_sel:[0,0,0] op_sel_hi:[0,1,1]
	v_add_f32_dpp v154, v154, v154 row_half_mirror row_mask:0xf bank_mask:0xf bound_ctrl:1
	s_nop 1
	v_add_f32_dpp v154, v154, v154 row_mirror row_mask:0xf bank_mask:0xf bound_ctrl:1
	v_pk_fma_f32 v[146:147], v[154:155], v[194:195], v[146:147] op_sel_hi:[0,1,1]
	v_pk_fma_f32 v[148:149], v[154:155], v[202:203], v[148:149] op_sel_hi:[0,1,1]
	s_waitcnt lgkmcnt(0)
	v_pk_mul_f32 v[150:151], v[146:147], v[206:207]
	v_pk_fma_f32 v[150:151], v[148:149], v[214:215], v[150:151]
	v_pk_mul_f32 v[152:153], v[146:147], v[228:229]
	v_add_f32_e32 v154, v150, v151
	v_pk_fma_f32 v[152:153], v[148:149], v[230:231], v[152:153]
	v_pk_mul_f32 v[142:143], v[146:147], v[208:209]
	v_add_f32_dpp v154, v154, v154 quad_perm:[1,0,3,2] row_mask:0xf bank_mask:0xf bound_ctrl:1
	v_pk_mul_f32 v[144:145], v[148:149], v[216:217]
	v_add_f32_e32 v170, v152, v153
	v_add_f32_dpp v154, v154, v154 quad_perm:[2,3,0,1] row_mask:0xf bank_mask:0xf bound_ctrl:1
	v_pk_fma_f32 v[142:143], v[242:243], v[212:213], v[142:143] op_sel:[1,0,0] op_sel_hi:[1,1,1]
	v_pk_fma_f32 v[144:145], v[242:243], v[220:221], v[144:145] op_sel:[1,0,0] op_sel_hi:[1,1,1]
	v_add_f32_dpp v154, v154, v154 row_half_mirror row_mask:0xf bank_mask:0xf bound_ctrl:1
	s_nop 1
	v_add_f32_dpp v154, v154, v154 row_mirror row_mask:0xf bank_mask:0xf bound_ctrl:1
	v_pk_fma_f32 v[142:143], v[154:155], v[210:211], v[142:143] op_sel_hi:[0,1,1]
	v_pk_fma_f32 v[144:145], v[154:155], v[218:219], v[144:145] op_sel_hi:[0,1,1]
	v_pk_mul_f32 v[152:153], v[142:143], v[232:233]
	v_pk_fma_f32 v[152:153], v[144:145], v[234:235], v[152:153]
	s_nop 0
	v_add_f32_e32 v171, v152, v153
	v_add_f32_dpp v172, v156, v156 row_ror:8 row_mask:0xf bank_mask:0x3
	v_add_f32_dpp v172, v164, v164 row_ror:8 row_mask:0xf bank_mask:0xc
	v_add_f32_dpp v173, v157, v157 row_ror:8 row_mask:0xf bank_mask:0x3
	v_add_f32_dpp v173, v165, v165 row_ror:8 row_mask:0xf bank_mask:0xc
	v_add_f32_dpp v174, v158, v158 row_ror:8 row_mask:0xf bank_mask:0x3
	v_add_f32_dpp v174, v166, v166 row_ror:8 row_mask:0xf bank_mask:0xc
	v_add_f32_dpp v175, v159, v159 row_ror:8 row_mask:0xf bank_mask:0x3
	v_add_f32_dpp v175, v167, v167 row_ror:8 row_mask:0xf bank_mask:0xc
	v_add_f32_dpp v176, v160, v160 row_ror:8 row_mask:0xf bank_mask:0x3
	v_add_f32_dpp v176, v168, v168 row_ror:8 row_mask:0xf bank_mask:0xc
	v_add_f32_dpp v177, v161, v161 row_ror:8 row_mask:0xf bank_mask:0x3
	v_add_f32_dpp v177, v169, v169 row_ror:8 row_mask:0xf bank_mask:0xc
	v_add_f32_dpp v178, v162, v162 row_ror:8 row_mask:0xf bank_mask:0x3
	v_add_f32_dpp v178, v170, v170 row_ror:8 row_mask:0xf bank_mask:0xc
	v_add_f32_dpp v179, v163, v163 row_ror:8 row_mask:0xf bank_mask:0x3
	v_add_f32_dpp v179, v171, v171 row_ror:8 row_mask:0xf bank_mask:0xc
	v_add_f32_dpp v156, v172, v172 row_half_mirror row_mask:0xf bank_mask:0x5
	v_add_f32_dpp v156, v176, v176 row_half_mirror row_mask:0xf bank_mask:0xa
	v_add_f32_dpp v157, v173, v173 row_half_mirror row_mask:0xf bank_mask:0x5
	v_add_f32_dpp v157, v177, v177 row_half_mirror row_mask:0xf bank_mask:0xa
	v_add_f32_dpp v158, v174, v174 row_half_mirror row_mask:0xf bank_mask:0x5
	v_add_f32_dpp v158, v178, v178 row_half_mirror row_mask:0xf bank_mask:0xa
	v_add_f32_dpp v159, v175, v175 row_half_mirror row_mask:0xf bank_mask:0x5
	v_add_f32_dpp v159, v179, v179 row_half_mirror row_mask:0xf bank_mask:0xa
	v_cndmask_b32_e64 v176, v158, v156, s[14:15]
	v_cndmask_b32_e64 v177, v159, v157, s[14:15]
	v_cndmask_b32_e64 v178, v156, v158, s[14:15]
	v_cndmask_b32_e64 v179, v157, v159, s[14:15]
	v_add_f32_dpp v172, v176, v178 quad_perm:[2,3,0,1] row_mask:0xf bank_mask:0xf
	v_add_f32_dpp v173, v177, v179 quad_perm:[2,3,0,1] row_mask:0xf bank_mask:0xf
	v_cndmask_b32_e64 v176, v173, v172, s[16:17]
	v_cndmask_b32_e64 v178, v172, v173, s[16:17]
	s_nop 0
	v_add_f32_dpp v181, v176, v178 quad_perm:[1,0,3,2] row_mask:0xf bank_mask:0xf
	ds_write2st64_b32 v187, v180, v181 offset0:0 offset1:4

; __device__ __forceinline__ void wkv_phase(const WkvT& W, unsigned char* lds) {
;     ...
;             if (c + 1 < 256) wkv_issue(W, raw, rowbase, cbase, q, c + 1, tid);
;             {
;                 const float* pp = sP + bo + jj * 12;
;                 const float* pv = sV + bi * 512 + il;
;                 f32x4 nA = *(const f32x4*)pp, nB = *(const f32x4*)(pp + 4); f32x2 nr = *(const f32x2*)(pp + 8); float nv = pv[0];
;                 float yk0 = 0.f, yk1 = 0.f, ep = 0.f;
;                 const bool oddrow = (lane & 16) != 0;
; #pragma unroll
;                 for (int t = 0; t < 32; ++t) {
;                     const f32x2 a2 = {nA[0], nA[1]}, w2 = {nA[2], nA[3]}, b2 = {nB[0], nB[1]}, k2 = {nB[2], nB[3]}, r2 = nr; const float v = nv;
;                     if (t + 1 < 32) { nA = *(const f32x4*)(pp + (t + 1) * 384); nB = *(const f32x4*)(pp + (t + 1) * 384 + 4); nr = *(const f32x2*)(pp + (t + 1) * 384 + 8); nv = pv[(t + 1) * 16]; }
;                     float S0 = S.x, S1 = S.y;
;                     float d = S0 * a2.x; d = __builtin_fmaf(S1, a2.y, d);
;                     float t0 = S0 * w2.x; t0 = __builtin_fmaf(v, k2.x, t0); asm volatile("" : "+v"(t0));
;                     float t1 = S1 * w2.y; t1 = __builtin_fmaf(v, k2.y, t1); asm volatile("" : "+v"(t1));
;                     float yprev; const float sa = wkv_reduce(d, ep, yprev);
;                     S0 = __builtin_fmaf(sa, b2.x, t0); asm volatile("" : "+v"(S0));
;                     S1 = __builtin_fmaf(sa, b2.y, t1); asm volatile("" : "+v"(S1));
;                     ep = S0 * r2.x; ep = __builtin_fmaf(S1, r2.y, ep);
;                     S.x = S0; S.y = S1;
.LBB0_1636:
	s_bitcmp1_b32 s99, 8
	s_cbranch_scc1 .Lwkv4_b2_skip
	ds_read_b128 v[190:193], v182 offset:49152
	ds_read_b128 v[194:197], v182 offset:49168
	ds_read_b64 v[228:229], v182 offset:49184
	ds_read_b128 v[198:201], v183 offset:49152
	ds_read_b128 v[202:205], v183 offset:49168
	ds_read_b64 v[230:231], v183 offset:49184
	ds_read2_b32 v[240:241], v226 offset0:0 offset1:16
	ds_read_b128 v[206:209], v182 offset:50688
	ds_read_b128 v[210:213], v182 offset:50704
	ds_read_b64 v[232:233], v182 offset:50720
	ds_read_b128 v[214:217], v183 offset:50688
	ds_read_b128 v[218:221], v183 offset:50704
	ds_read_b64 v[234:235], v183 offset:50720
	s_waitcnt lgkmcnt(6)
	v_pk_mul_f32 v[150:151], v[142:143], v[190:191]
	v_pk_fma_f32 v[150:151], v[144:145], v[198:199], v[150:151]
	v_pk_mul_f32 v[146:147], v[142:143], v[192:193]
	v_add_f32_e32 v154, v150, v151
	v_pk_mul_f32 v[148:149], v[144:145], v[200:201]
	v_pk_fma_f32 v[146:147], v[240:241], v[196:197], v[146:147] op_sel:[0,0,0] op_sel_hi:[0,1,1]
	v_add_f32_dpp v154, v154, v154 quad_perm:[1,0,3,2] row_mask:0xf bank_mask:0xf bound_ctrl:1
	v_pk_fma_f32 v[148:149], v[240:241], v[204:205], v[148:149] op_sel:[0,0,0] op_sel_hi:[0,1,1]
	s_nop 0
	v_add_f32_dpp v154, v154, v154 quad_perm:[2,3,0,1] row_mask:0xf bank_mask:0xf bound_ctrl:1
	ds_read_b128 v[126:129], v182 offset:52224
	ds_read_b128 v[130:133], v182 offset:52240
	v_add_f32_dpp v154, v154, v154 row_half_mirror row_mask:0xf bank_mask:0xf bound_ctrl:1
	ds_read_b64 v[236:237], v182 offset:52256
	ds_read_b128 v[134:137], v183 offset:52224
	v_add_f32_dpp v154, v154, v154 row_mirror row_mask:0xf bank_mask:0xf bound_ctrl:1
	v_pk_fma_f32 v[146:147], v[154:155], v[194:195], v[146:147] op_sel_hi:[0,1,1]
	v_pk_fma_f32 v[148:149], v[154:155], v[202:203], v[148:149] op_sel_hi:[0,1,1]
	ds_read_b128 v[222:225], v183 offset:52240
	ds_read_b64 v[238:239], v183 offset:52256
	ds_read2_b32 v[242:243], v226 offset0:32 offset1:48
	s_waitcnt lgkmcnt(7)
	v_pk_mul_f32 v[150:151], v[146:147], v[206:207]
	v_pk_fma_f32 v[150:151], v[148:149], v[214:215], v[150:151]
	v_pk_mul_f32 v[152:153], v[146:147], v[228:229]
	v_add_f32_e32 v154, v150, v151
	v_pk_fma_f32 v[152:153], v[148:149], v[230:231], v[152:153]
	v_pk_mul_f32 v[142:143], v[146:147], v[208:209]
	v_add_f32_dpp v154, v154, v154 quad_perm:[1,0,3,2] row_mask:0xf bank_mask:0xf bound_ctrl:1
	v_pk_mul_f32 v[144:145], v[148:149], v[216:217]
	v_add_f32_e32 v156, v152, v153
	v_add_f32_dpp v154, v154, v154 quad_perm:[2,3,0,1] row_mask:0xf bank_mask:0xf bound_ctrl:1
	v_pk_fma_f32 v[142:143], v[240:241], v[212:213], v[142:143] op_sel:[1,0,0] op_sel_hi:[1,1,1]
	v_pk_fma_f32 v[144:145], v[240:241], v[220:221], v[144:145] op_sel:[1,0,0] op_sel_hi:[1,1,1]
	v_add_f32_dpp v154, v154, v154 row_half_mirror row_mask:0xf bank_mask:0xf bound_ctrl:1
	ds_read_b128 v[190:193], v182 offset:53760
	ds_read_b128 v[194:197], v182 offset:53776
	v_add_f32_dpp v154, v154, v154 row_mirror row_mask:0xf bank_mask:0xf bound_ctrl:1
	ds_read_b64 v[228:229], v182 offset:53792
	v_pk_fma_f32 v[142:143], v[154:155], v[210:211], v[142:143] op_sel_hi:[0,1,1]
	v_pk_fma_f32 v[144:145], v[154:155], v[218:219], v[144:145] op_sel_hi:[0,1,1]
	ds_read_b128 v[198:201], v183 offset:53760
	ds_read_b128 v[202:205], v183 offset:53776
	ds_read_b64 v[230:231], v183 offset:53792
	s_waitcnt lgkmcnt(6)
	v_pk_mul_f32 v[150:151], v[142:143], v[126:127]
	v_pk_fma_f32 v[150:151], v[144:145], v[134:135], v[150:151]
	v_pk_mul_f32 v[152:153], v[142:143], v[232:233]
	v_add_f32_e32 v154, v150, v151
	v_pk_fma_f32 v[152:153], v[144:145], v[234:235], v[152:153]
	v_pk_mul_f32 v[146:147], v[142:143], v[128:129]
	v_add_f32_dpp v154, v154, v154 quad_perm:[1,0,3,2] row_mask:0xf bank_mask:0xf bound_ctrl:1
	v_pk_mul_f32 v[148:149], v[144:145], v[136:137]
	v_add_f32_e32 v157, v152, v153
	v_add_f32_dpp v154, v154, v154 quad_perm:[2,3,0,1] row_mask:0xf bank_mask:0xf bound_ctrl:1
	v_pk_fma_f32 v[146:147], v[242:243], v[132:133], v[146:147] op_sel:[0,0,0] op_sel_hi:[0,1,1]
	v_pk_fma_f32 v[148:149], v[242:243], v[224:225], v[148:149] op_sel:[0,0,0] op_sel_hi:[0,1,1]
	v_add_f32_dpp v154, v154, v154 row_half_mirror row_mask:0xf bank_mask:0xf bound_ctrl:1
	ds_read_b128 v[206:209], v182 offset:55296
	ds_read_b128 v[210:213], v182 offset:55312
	v_add_f32_dpp v154, v154, v154 row_mirror row_mask:0xf bank_mask:0xf bound_ctrl:1
	ds_read_b64 v[232:233], v182 offset:55328
	ds_read_b128 v[214:217], v183 offset:55296
	v_pk_fma_f32 v[146:147], v[154:155], v[130:131], v[146:147] op_sel_hi:[0,1,1]
	v_pk_fma_f32 v[148:149], v[154:155], v[222:223], v[148:149] op_sel_hi:[0,1,1]
	ds_read_b128 v[218:221], v183 offset:55312
	ds_read_b64 v[234:235], v183 offset:55328
	ds_read2_b32 v[240:241], v226 offset0:64 offset1:80
	s_waitcnt lgkmcnt(7)
	v_pk_mul_f32 v[150:151], v[146:147], v[190:191]
	v_pk_fma_f32 v[150:151], v[148:149], v[198:199], v[150:151]
	v_pk_mul_f32 v[152:153], v[146:147], v[236:237]
	v_add_f32_e32 v154, v150, v151
	v_pk_fma_f32 v[152:153], v[148:149], v[238:239], v[152:153]
	v_pk_mul_f32 v[142:143], v[146:147], v[192:193]
	v_add_f32_dpp v154, v154, v154 quad_perm:[1,0,3,2] row_mask:0xf bank_mask:0xf bound_ctrl:1
	v_pk_mul_f32 v[144:145], v[148:149], v[200:201]
	v_add_f32_e32 v158, v152, v153
	v_add_f32_dpp v154, v154, v154 quad_perm:[2,3,0,1] row_mask:0xf bank_mask:0xf bound_ctrl:1
	v_pk_fma_f32 v[142:143], v[242:243], v[196:197], v[142:143] op_sel:[1,0,0] op_sel_hi:[1,1,1]
	v_pk_fma_f32 v[144:145], v[242:243], v[204:205], v[144:145] op_sel:[1,0,0] op_sel_hi:[1,1,1]
	v_add_f32_dpp v154, v154, v154 row_half_mirror row_mask:0xf bank_mask:0xf bound_ctrl:1
	ds_read_b128 v[126:129], v182 offset:56832
	ds_read_b128 v[130:133], v182 offset:56848
	v_add_f32_dpp v154, v154, v154 row_mirror row_mask:0xf bank_mask:0xf bound_ctrl:1
	ds_read_b64 v[236:237], v182 offset:56864
	v_pk_fma_f32 v[142:143], v[154:155], v[194:195], v[142:143] op_sel_hi:[0,1,1]
	v_pk_fma_f32 v[144:145], v[154:155], v[202:203], v[144:145] op_sel_hi:[0,1,1]
	ds_read_b128 v[134:137], v183 offset:56832
	ds_read_b128 v[222:225], v183 offset:56848
	ds_read_b64 v[238:239], v183 offset:56864
	s_waitcnt lgkmcnt(6)
; __device__ __forceinline__ void wkv_phase(const WkvT& W, unsigned char* lds) {
;     ...
;                 const float* pp = sP + bo + jj * 12;
;                 const float* pv = sV + bi * 512 + il;
;                 f32x4 nA = *(const f32x4*)pp, nB = *(const f32x4*)(pp + 4); f32x2 nr = *(const f32x2*)(pp + 8); float nv = pv[0];
;                 float yk0 = 0.f, yk1 = 0.f, ep = 0.f;
;                 const bool oddrow = (lane & 16) != 0;
; #pragma unroll
;                 for (int t = 0; t < 32; ++t) {
;                     const f32x2 a2 = {nA[0], nA[1]}, w2 = {nA[2], nA[3]}, b2 = {nB[0], nB[1]}, k2 = {nB[2], nB[3]}, r2 = nr; const float v = nv;
;                     if (t + 1 < 32) { nA = *(const f32x4*)(pp + (t + 1) * 384); nB = *(const f32x4*)(pp + (t + 1) * 384 + 4); nr = *(const f32x2*)(pp + (t + 1) * 384 + 8); nv = pv[(t + 1) * 16]; }
;                     float S0 = S.x, S1 = S.y;
;                     float d = S0 * a2.x; d = __builtin_fmaf(S1, a2.y, d);
;                     float t0 = S0 * w2.x; t0 = __builtin_fmaf(v, k2.x, t0); asm volatile("" : "+v"(t0));
;                     float t1 = S1 * w2.y; t1 = __builtin_fmaf(v, k2.y, t1); asm volatile("" : "+v"(t1));
;                     float yprev; const float sa = wkv_reduce(d, ep, yprev);
;                     S0 = __builtin_fmaf(sa, b2.x, t0); asm volatile("" : "+v"(S0));
;                     S1 = __builtin_fmaf(sa, b2.y, t1); asm volatile("" : "+v"(S1));
;                     ep = S0 * r2.x; ep = __builtin_fmaf(S1, r2.y, ep);
;                     S.x = S0; S.y = S1;
	v_pk_mul_f32 v[150:151], v[142:143], v[206:207]
	v_pk_fma_f32 v[150:151], v[144:145], v[214:215], v[150:151]
	v_pk_mul_f32 v[152:153], v[142:143], v[228:229]
	v_add_f32_e32 v154, v150, v151
	v_pk_fma_f32 v[152:153], v[144:145], v[230:231], v[152:153]
	v_pk_mul_f32 v[146:147], v[142:143], v[208:209]
	v_add_f32_dpp v154, v154, v154 quad_perm:[1,0,3,2] row_mask:0xf bank_mask:0xf bound_ctrl:1
	v_pk_mul_f32 v[148:149], v[144:145], v[216:217]
	v_add_f32_e32 v159, v152, v153
	v_add_f32_dpp v154, v154, v154 quad_perm:[2,3,0,1] row_mask:0xf bank_mask:0xf bound_ctrl:1
	v_pk_fma_f32 v[146:147], v[240:241], v[212:213], v[146:147] op_sel:[0,0,0] op_sel_hi:[0,1,1]
	v_pk_fma_f32 v[148:149], v[240:241], v[220:221], v[148:149] op_sel:[0,0,0] op_sel_hi:[0,1,1]
	v_add_f32_dpp v154, v154, v154 row_half_mirror row_mask:0xf bank_mask:0xf bound_ctrl:1
	ds_read_b128 v[190:193], v182 offset:58368
	ds_read_b128 v[194:197], v182 offset:58384
	v_add_f32_dpp v154, v154, v154 row_mirror row_mask:0xf bank_mask:0xf bound_ctrl:1
	ds_read_b64 v[228:229], v182 offset:58400
	ds_read_b128 v[198:201], v183 offset:58368
	v_pk_fma_f32 v[146:147], v[154:155], v[210:211], v[146:147] op_sel_hi:[0,1,1]
	v_pk_fma_f32 v[148:149], v[154:155], v[218:219], v[148:149] op_sel_hi:[0,1,1]
	ds_read_b128 v[202:205], v183 offset:58384
	ds_read_b64 v[230:231], v183 offset:58400
	ds_read2_b32 v[242:243], v226 offset0:96 offset1:112
	s_waitcnt lgkmcnt(7)
	v_pk_mul_f32 v[150:151], v[146:147], v[126:127]
	v_pk_fma_f32 v[150:151], v[148:149], v[134:135], v[150:151]
	v_pk_mul_f32 v[152:153], v[146:147], v[232:233]
	v_add_f32_e32 v154, v150, v151
	v_pk_fma_f32 v[152:153], v[148:149], v[234:235], v[152:153]
	v_pk_mul_f32 v[142:143], v[146:147], v[128:129]
	v_add_f32_dpp v154, v154, v154 quad_perm:[1,0,3,2] row_mask:0xf bank_mask:0xf bound_ctrl:1
	v_pk_mul_f32 v[144:145], v[148:149], v[136:137]
	v_add_f32_e32 v160, v152, v153
	v_add_f32_dpp v154, v154, v154 quad_perm:[2,3,0,1] row_mask:0xf bank_mask:0xf bound_ctrl:1
	v_pk_fma_f32 v[142:143], v[240:241], v[132:133], v[142:143] op_sel:[1,0,0] op_sel_hi:[1,1,1]
	v_pk_fma_f32 v[144:145], v[240:241], v[224:225], v[144:145] op_sel:[1,0,0] op_sel_hi:[1,1,1]
	v_add_f32_dpp v154, v154, v154 row_half_mirror row_mask:0xf bank_mask:0xf bound_ctrl:1
	ds_read_b128 v[206:209], v182 offset:59904
	ds_read_b128 v[210:213], v182 offset:59920
	v_add_f32_dpp v154, v154, v154 row_mirror row_mask:0xf bank_mask:0xf bound_ctrl:1
	ds_read_b64 v[232:233], v182 offset:59936
	v_pk_fma_f32 v[142:143], v[154:155], v[130:131], v[142:143] op_sel_hi:[0,1,1]
	v_pk_fma_f32 v[144:145], v[154:155], v[222:223], v[144:145] op_sel_hi:[0,1,1]
	ds_read_b128 v[214:217], v183 offset:59904
	ds_read_b128 v[218:221], v183 offset:59920
	ds_read_b64 v[234:235], v183 offset:59936
	s_waitcnt lgkmcnt(6)
	v_pk_mul_f32 v[150:151], v[142:143], v[190:191]
	v_pk_fma_f32 v[150:151], v[144:145], v[198:199], v[150:151]
	v_pk_mul_f32 v[152:153], v[142:143], v[236:237]
	v_add_f32_e32 v154, v150, v151
	v_pk_fma_f32 v[152:153], v[144:145], v[238:239], v[152:153]
	v_pk_mul_f32 v[146:147], v[142:143], v[192:193]
	v_add_f32_dpp v154, v154, v154 quad_perm:[1,0,3,2] row_mask:0xf bank_mask:0xf bound_ctrl:1
	v_pk_mul_f32 v[148:149], v[144:145], v[200:201]
	v_add_f32_e32 v161, v152, v153
	v_add_f32_dpp v154, v154, v154 quad_perm:[2,3,0,1] row_mask:0xf bank_mask:0xf bound_ctrl:1
	v_pk_fma_f32 v[146:147], v[242:243], v[196:197], v[146:147] op_sel:[0,0,0] op_sel_hi:[0,1,1]
	v_pk_fma_f32 v[148:149], v[242:243], v[204:205], v[148:149] op_sel:[0,0,0] op_sel_hi:[0,1,1]
	v_add_f32_dpp v154, v154, v154 row_half_mirror row_mask:0xf bank_mask:0xf bound_ctrl:1
	ds_read_b128 v[126:129], v182 offset:61440
	ds_read_b128 v[130:133], v182 offset:61456
	v_add_f32_dpp v154, v154, v154 row_mirror row_mask:0xf bank_mask:0xf bound_ctrl:1
	ds_read_b64 v[236:237], v182 offset:61472
	ds_read_b128 v[134:137], v183 offset:61440
	v_pk_fma_f32 v[146:147], v[154:155], v[194:195], v[146:147] op_sel_hi:[0,1,1]
	v_pk_fma_f32 v[148:149], v[154:155], v[202:203], v[148:149] op_sel_hi:[0,1,1]
	ds_read_b128 v[222:225], v183 offset:61456
	ds_read_b64 v[238:239], v183 offset:61472
	ds_read2_b32 v[240:241], v226 offset0:128 offset1:144
	s_waitcnt lgkmcnt(7)
	v_pk_mul_f32 v[150:151], v[146:147], v[206:207]
	v_pk_fma_f32 v[150:151], v[148:149], v[214:215], v[150:151]
	v_pk_mul_f32 v[152:153], v[146:147], v[228:229]
	v_add_f32_e32 v154, v150, v151
	v_pk_fma_f32 v[152:153], v[148:149], v[230:231], v[152:153]
	v_pk_mul_f32 v[142:143], v[146:147], v[208:209]
	v_add_f32_dpp v154, v154, v154 quad_perm:[1,0,3,2] row_mask:0xf bank_mask:0xf bound_ctrl:1
	v_pk_mul_f32 v[144:145], v[148:149], v[216:217]
	v_add_f32_e32 v162, v152, v153
	v_add_f32_dpp v154, v154, v154 quad_perm:[2,3,0,1] row_mask:0xf bank_mask:0xf bound_ctrl:1
	v_pk_fma_f32 v[142:143], v[242:243], v[212:213], v[142:143] op_sel:[1,0,0] op_sel_hi:[1,1,1]
	v_pk_fma_f32 v[144:145], v[242:243], v[220:221], v[144:145] op_sel:[1,0,0] op_sel_hi:[1,1,1]
	v_add_f32_dpp v154, v154, v154 row_half_mirror row_mask:0xf bank_mask:0xf bound_ctrl:1
	ds_read_b128 v[190:193], v182 offset:62976
	ds_read_b128 v[194:197], v182 offset:62992
	v_add_f32_dpp v154, v154, v154 row_mirror row_mask:0xf bank_mask:0xf bound_ctrl:1
	ds_read_b64 v[228:229], v182 offset:63008
	v_pk_fma_f32 v[142:143], v[154:155], v[210:211], v[142:143] op_sel_hi:[0,1,1]
	v_pk_fma_f32 v[144:145], v[154:155], v[218:219], v[144:145] op_sel_hi:[0,1,1]
	ds_read_b128 v[198:201], v183 offset:62976
	ds_read_b128 v[202:205], v183 offset:62992
	ds_read_b64 v[230:231], v183 offset:63008
	s_waitcnt lgkmcnt(6)
; __device__ __forceinline__ void wkv_phase(const WkvT& W, unsigned char* lds) {
;     ...
;                 const float* pp = sP + bo + jj * 12;
;                 const float* pv = sV + bi * 512 + il;
;                 f32x4 nA = *(const f32x4*)pp, nB = *(const f32x4*)(pp + 4); f32x2 nr = *(const f32x2*)(pp + 8); float nv = pv[0];
;                 float yk0 = 0.f, yk1 = 0.f, ep = 0.f;
;                 const bool oddrow = (lane & 16) != 0;
; #pragma unroll
;                 for (int t = 0; t < 32; ++t) {
;                     const f32x2 a2 = {nA[0], nA[1]}, w2 = {nA[2], nA[3]}, b2 = {nB[0], nB[1]}, k2 = {nB[2], nB[3]}, r2 = nr; const float v = nv;
;                     if (t + 1 < 32) { nA = *(const f32x4*)(pp + (t + 1) * 384); nB = *(const f32x4*)(pp + (t + 1) * 384 + 4); nr = *(const f32x2*)(pp + (t + 1) * 384 + 8); nv = pv[(t + 1) * 16]; }
;                     float S0 = S.x, S1 = S.y;
;                     float d = S0 * a2.x; d = __builtin_fmaf(S1, a2.y, d);
;                     float t0 = S0 * w2.x; t0 = __builtin_fmaf(v, k2.x, t0); asm volatile("" : "+v"(t0));
;                     float t1 = S1 * w2.y; t1 = __builtin_fmaf(v, k2.y, t1); asm volatile("" : "+v"(t1));
;                     float yprev; const float sa = wkv_reduce(d, ep, yprev);
;                     S0 = __builtin_fmaf(sa, b2.x, t0); asm volatile("" : "+v"(S0));
;                     S1 = __builtin_fmaf(sa, b2.y, t1); asm volatile("" : "+v"(S1));
;                     ep = S0 * r2.x; ep = __builtin_fmaf(S1, r2.y, ep);
;                     S.x = S0; S.y = S1;
	v_pk_mul_f32 v[150:151], v[142:143], v[126:127]
	v_pk_fma_f32 v[150:151], v[144:145], v[134:135], v[150:151]
	v_pk_mul_f32 v[152:153], v[142:143], v[232:233]
	v_add_f32_e32 v154, v150, v151
	v_pk_fma_f32 v[152:153], v[144:145], v[234:235], v[152:153]
	v_pk_mul_f32 v[146:147], v[142:143], v[128:129]
	v_add_f32_dpp v154, v154, v154 quad_perm:[1,0,3,2] row_mask:0xf bank_mask:0xf bound_ctrl:1
	v_pk_mul_f32 v[148:149], v[144:145], v[136:137]
	v_add_f32_e32 v163, v152, v153
	v_add_f32_dpp v154, v154, v154 quad_perm:[2,3,0,1] row_mask:0xf bank_mask:0xf bound_ctrl:1
	v_pk_fma_f32 v[146:147], v[240:241], v[132:133], v[146:147] op_sel:[0,0,0] op_sel_hi:[0,1,1]
	v_pk_fma_f32 v[148:149], v[240:241], v[224:225], v[148:149] op_sel:[0,0,0] op_sel_hi:[0,1,1]
	v_add_f32_dpp v154, v154, v154 row_half_mirror row_mask:0xf bank_mask:0xf bound_ctrl:1
	ds_read_b128 v[206:209], v182 offset:64512
	ds_read_b128 v[210:213], v182 offset:64528
	v_add_f32_dpp v154, v154, v154 row_mirror row_mask:0xf bank_mask:0xf bound_ctrl:1
	ds_read_b64 v[232:233], v182 offset:64544
	ds_read_b128 v[214:217], v183 offset:64512
	v_pk_fma_f32 v[146:147], v[154:155], v[130:131], v[146:147] op_sel_hi:[0,1,1]
	v_pk_fma_f32 v[148:149], v[154:155], v[222:223], v[148:149] op_sel_hi:[0,1,1]
	ds_read_b128 v[218:221], v183 offset:64528
	ds_read_b64 v[234:235], v183 offset:64544
	ds_read2_b32 v[242:243], v226 offset0:160 offset1:176
	s_waitcnt lgkmcnt(7)
	v_pk_mul_f32 v[150:151], v[146:147], v[190:191]
	v_pk_fma_f32 v[150:151], v[148:149], v[198:199], v[150:151]
	v_pk_mul_f32 v[152:153], v[146:147], v[236:237]
	v_add_f32_e32 v154, v150, v151
	v_pk_fma_f32 v[152:153], v[148:149], v[238:239], v[152:153]
	v_pk_mul_f32 v[142:143], v[146:147], v[192:193]
	v_add_f32_dpp v154, v154, v154 quad_perm:[1,0,3,2] row_mask:0xf bank_mask:0xf bound_ctrl:1
	v_pk_mul_f32 v[144:145], v[148:149], v[200:201]
	v_add_f32_e32 v164, v152, v153
	v_add_f32_dpp v154, v154, v154 quad_perm:[2,3,0,1] row_mask:0xf bank_mask:0xf bound_ctrl:1
	v_pk_fma_f32 v[142:143], v[240:241], v[196:197], v[142:143] op_sel:[1,0,0] op_sel_hi:[1,1,1]
	v_pk_fma_f32 v[144:145], v[240:241], v[204:205], v[144:145] op_sel:[1,0,0] op_sel_hi:[1,1,1]
	v_add_f32_dpp v154, v154, v154 row_half_mirror row_mask:0xf bank_mask:0xf bound_ctrl:1
	ds_read_b128 v[126:129], v184
	ds_read_b128 v[130:133], v184 offset:16
	v_add_f32_dpp v154, v154, v154 row_mirror row_mask:0xf bank_mask:0xf bound_ctrl:1
	ds_read_b64 v[236:237], v184 offset:32
	v_pk_fma_f32 v[142:143], v[154:155], v[194:195], v[142:143] op_sel_hi:[0,1,1]
	v_pk_fma_f32 v[144:145], v[154:155], v[202:203], v[144:145] op_sel_hi:[0,1,1]
	ds_read_b128 v[134:137], v185
	ds_read_b128 v[222:225], v185 offset:16
	ds_read_b64 v[238:239], v185 offset:32
	s_waitcnt lgkmcnt(6)
	v_pk_mul_f32 v[150:151], v[142:143], v[206:207]
	v_pk_fma_f32 v[150:151], v[144:145], v[214:215], v[150:151]
	v_pk_mul_f32 v[152:153], v[142:143], v[228:229]
	v_add_f32_e32 v154, v150, v151
	v_pk_fma_f32 v[152:153], v[144:145], v[230:231], v[152:153]
	v_pk_mul_f32 v[146:147], v[142:143], v[208:209]
	v_add_f32_dpp v154, v154, v154 quad_perm:[1,0,3,2] row_mask:0xf bank_mask:0xf bound_ctrl:1
	v_pk_mul_f32 v[148:149], v[144:145], v[216:217]
	v_add_f32_e32 v165, v152, v153
	v_add_f32_dpp v154, v154, v154 quad_perm:[2,3,0,1] row_mask:0xf bank_mask:0xf bound_ctrl:1
	v_pk_fma_f32 v[146:147], v[242:243], v[212:213], v[146:147] op_sel:[0,0,0] op_sel_hi:[0,1,1]
	v_pk_fma_f32 v[148:149], v[242:243], v[220:221], v[148:149] op_sel:[0,0,0] op_sel_hi:[0,1,1]
	v_add_f32_dpp v154, v154, v154 row_half_mirror row_mask:0xf bank_mask:0xf bound_ctrl:1
	ds_read_b128 v[190:193], v184 offset:1536
	ds_read_b128 v[194:197], v184 offset:1552
	v_add_f32_dpp v154, v154, v154 row_mirror row_mask:0xf bank_mask:0xf bound_ctrl:1
	ds_read_b64 v[228:229], v184 offset:1568
	ds_read_b128 v[198:201], v185 offset:1536
	v_pk_fma_f32 v[146:147], v[154:155], v[210:211], v[146:147] op_sel_hi:[0,1,1]
	v_pk_fma_f32 v[148:149], v[154:155], v[218:219], v[148:149] op_sel_hi:[0,1,1]
	ds_read_b128 v[202:205], v185 offset:1552
	ds_read_b64 v[230:231], v185 offset:1568
	ds_read2_b32 v[240:241], v226 offset0:192 offset1:208
	s_waitcnt lgkmcnt(7)
	v_pk_mul_f32 v[150:151], v[146:147], v[126:127]
	v_pk_fma_f32 v[150:151], v[148:149], v[134:135], v[150:151]
	v_pk_mul_f32 v[152:153], v[146:147], v[232:233]
	v_add_f32_e32 v154, v150, v151
	v_pk_fma_f32 v[152:153], v[148:149], v[234:235], v[152:153]
	v_pk_mul_f32 v[142:143], v[146:147], v[128:129]
	v_add_f32_dpp v154, v154, v154 quad_perm:[1,0,3,2] row_mask:0xf bank_mask:0xf bound_ctrl:1
	v_pk_mul_f32 v[144:145], v[148:149], v[136:137]
	v_add_f32_e32 v166, v152, v153
	v_add_f32_dpp v154, v154, v154 quad_perm:[2,3,0,1] row_mask:0xf bank_mask:0xf bound_ctrl:1
	v_pk_fma_f32 v[142:143], v[242:243], v[132:133], v[142:143] op_sel:[1,0,0] op_sel_hi:[1,1,1]
	v_pk_fma_f32 v[144:145], v[242:243], v[224:225], v[144:145] op_sel:[1,0,0] op_sel_hi:[1,1,1]
	v_add_f32_dpp v154, v154, v154 row_half_mirror row_mask:0xf bank_mask:0xf bound_ctrl:1
	ds_read_b128 v[206:209], v184 offset:3072
	ds_read_b128 v[210:213], v184 offset:3088
	v_add_f32_dpp v154, v154, v154 row_mirror row_mask:0xf bank_mask:0xf bound_ctrl:1
	ds_read_b64 v[232:233], v184 offset:3104
	v_pk_fma_f32 v[142:143], v[154:155], v[130:131], v[142:143] op_sel_hi:[0,1,1]
	v_pk_fma_f32 v[144:145], v[154:155], v[222:223], v[144:145] op_sel_hi:[0,1,1]
	ds_read_b128 v[214:217], v185 offset:3072
	ds_read_b128 v[218:221], v185 offset:3088
	ds_read_b64 v[234:235], v185 offset:3104
	s_waitcnt lgkmcnt(6)
; __device__ __forceinline__ void wkv_phase(const WkvT& W, unsigned char* lds) {
;     ...
;                 const float* pp = sP + bo + jj * 12;
;                 const float* pv = sV + bi * 512 + il;
;                 f32x4 nA = *(const f32x4*)pp, nB = *(const f32x4*)(pp + 4); f32x2 nr = *(const f32x2*)(pp + 8); float nv = pv[0];
;                 float yk0 = 0.f, yk1 = 0.f, ep = 0.f;
;                 const bool oddrow = (lane & 16) != 0;
; #pragma unroll
;                 for (int t = 0; t < 32; ++t) {
;                     const f32x2 a2 = {nA[0], nA[1]}, w2 = {nA[2], nA[3]}, b2 = {nB[0], nB[1]}, k2 = {nB[2], nB[3]}, r2 = nr; const float v = nv;
;                     if (t + 1 < 32) { nA = *(const f32x4*)(pp + (t + 1) * 384); nB = *(const f32x4*)(pp + (t + 1) * 384 + 4); nr = *(const f32x2*)(pp + (t + 1) * 384 + 8); nv = pv[(t + 1) * 16]; }
;                     float S0 = S.x, S1 = S.y;
;                     float d = S0 * a2.x; d = __builtin_fmaf(S1, a2.y, d);
;                     float t0 = S0 * w2.x; t0 = __builtin_fmaf(v, k2.x, t0); asm volatile("" : "+v"(t0));
;                     float t1 = S1 * w2.y; t1 = __builtin_fmaf(v, k2.y, t1); asm volatile("" : "+v"(t1));
;                     float yprev; const float sa = wkv_reduce(d, ep, yprev);
;                     S0 = __builtin_fmaf(sa, b2.x, t0); asm volatile("" : "+v"(S0));
;                     S1 = __builtin_fmaf(sa, b2.y, t1); asm volatile("" : "+v"(S1));
;                     ep = S0 * r2.x; ep = __builtin_fmaf(S1, r2.y, ep);
;                     S.x = S0; S.y = S1;
	v_pk_mul_f32 v[150:151], v[142:143], v[190:191]
	v_pk_fma_f32 v[150:151], v[144:145], v[198:199], v[150:151]
	v_pk_mul_f32 v[152:153], v[142:143], v[236:237]
	v_add_f32_e32 v154, v150, v151
	v_pk_fma_f32 v[152:153], v[144:145], v[238:239], v[152:153]
	v_pk_mul_f32 v[146:147], v[142:143], v[192:193]
	v_add_f32_dpp v154, v154, v154 quad_perm:[1,0,3,2] row_mask:0xf bank_mask:0xf bound_ctrl:1
	v_pk_mul_f32 v[148:149], v[144:145], v[200:201]
	v_add_f32_e32 v167, v152, v153
	v_add_f32_dpp v154, v154, v154 quad_perm:[2,3,0,1] row_mask:0xf bank_mask:0xf bound_ctrl:1
	v_pk_fma_f32 v[146:147], v[240:241], v[196:197], v[146:147] op_sel:[0,0,0] op_sel_hi:[0,1,1]
	v_pk_fma_f32 v[148:149], v[240:241], v[204:205], v[148:149] op_sel:[0,0,0] op_sel_hi:[0,1,1]
	v_add_f32_dpp v154, v154, v154 row_half_mirror row_mask:0xf bank_mask:0xf bound_ctrl:1
	ds_read_b128 v[126:129], v184 offset:4608
	ds_read_b128 v[130:133], v184 offset:4624
	v_add_f32_dpp v154, v154, v154 row_mirror row_mask:0xf bank_mask:0xf bound_ctrl:1
	ds_read_b64 v[236:237], v184 offset:4640
	ds_read_b128 v[134:137], v185 offset:4608
	v_pk_fma_f32 v[146:147], v[154:155], v[194:195], v[146:147] op_sel_hi:[0,1,1]
	v_pk_fma_f32 v[148:149], v[154:155], v[202:203], v[148:149] op_sel_hi:[0,1,1]
	ds_read_b128 v[222:225], v185 offset:4624
	ds_read_b64 v[238:239], v185 offset:4640
	ds_read2_b32 v[242:243], v226 offset0:224 offset1:240
	s_waitcnt lgkmcnt(7)
	v_pk_mul_f32 v[150:151], v[146:147], v[206:207]
	v_pk_fma_f32 v[150:151], v[148:149], v[214:215], v[150:151]
	v_pk_mul_f32 v[152:153], v[146:147], v[228:229]
	v_add_f32_e32 v154, v150, v151
	v_pk_fma_f32 v[152:153], v[148:149], v[230:231], v[152:153]
	v_pk_mul_f32 v[142:143], v[146:147], v[208:209]
	v_add_f32_dpp v154, v154, v154 quad_perm:[1,0,3,2] row_mask:0xf bank_mask:0xf bound_ctrl:1
	v_pk_mul_f32 v[144:145], v[148:149], v[216:217]
	v_add_f32_e32 v168, v152, v153
	v_add_f32_dpp v154, v154, v154 quad_perm:[2,3,0,1] row_mask:0xf bank_mask:0xf bound_ctrl:1
	v_pk_fma_f32 v[142:143], v[240:241], v[212:213], v[142:143] op_sel:[1,0,0] op_sel_hi:[1,1,1]
	v_pk_fma_f32 v[144:145], v[240:241], v[220:221], v[144:145] op_sel:[1,0,0] op_sel_hi:[1,1,1]
	v_add_f32_dpp v154, v154, v154 row_half_mirror row_mask:0xf bank_mask:0xf bound_ctrl:1
	ds_read_b128 v[190:193], v184 offset:6144
	ds_read_b128 v[194:197], v184 offset:6160
	v_add_f32_dpp v154, v154, v154 row_mirror row_mask:0xf bank_mask:0xf bound_ctrl:1
	ds_read_b64 v[228:229], v184 offset:6176
	v_pk_fma_f32 v[142:143], v[154:155], v[210:211], v[142:143] op_sel_hi:[0,1,1]
	v_pk_fma_f32 v[144:145], v[154:155], v[218:219], v[144:145] op_sel_hi:[0,1,1]
	ds_read_b128 v[198:201], v185 offset:6144
	ds_read_b128 v[202:205], v185 offset:6160
	ds_read_b64 v[230:231], v185 offset:6176
	s_waitcnt lgkmcnt(6)
	v_pk_mul_f32 v[150:151], v[142:143], v[126:127]
	v_pk_fma_f32 v[150:151], v[144:145], v[134:135], v[150:151]
	v_pk_mul_f32 v[152:153], v[142:143], v[232:233]
	v_add_f32_e32 v154, v150, v151
	v_pk_fma_f32 v[152:153], v[144:145], v[234:235], v[152:153]
	v_pk_mul_f32 v[146:147], v[142:143], v[128:129]
	v_add_f32_dpp v154, v154, v154 quad_perm:[1,0,3,2] row_mask:0xf bank_mask:0xf bound_ctrl:1
	v_pk_mul_f32 v[148:149], v[144:145], v[136:137]
	v_add_f32_e32 v169, v152, v153
	v_add_f32_dpp v154, v154, v154 quad_perm:[2,3,0,1] row_mask:0xf bank_mask:0xf bound_ctrl:1
	v_pk_fma_f32 v[146:147], v[242:243], v[132:133], v[146:147] op_sel:[0,0,0] op_sel_hi:[0,1,1]
	v_pk_fma_f32 v[148:149], v[242:243], v[224:225], v[148:149] op_sel:[0,0,0] op_sel_hi:[0,1,1]
	v_add_f32_dpp v154, v154, v154 row_half_mirror row_mask:0xf bank_mask:0xf bound_ctrl:1
	ds_read_b128 v[206:209], v184 offset:7680
	ds_read_b128 v[210:213], v184 offset:7696
	v_add_f32_dpp v154, v154, v154 row_mirror row_mask:0xf bank_mask:0xf bound_ctrl:1
	ds_read_b64 v[232:233], v184 offset:7712
	ds_read_b128 v[214:217], v185 offset:7680
	v_pk_fma_f32 v[146:147], v[154:155], v[130:131], v[146:147] op_sel_hi:[0,1,1]
	v_pk_fma_f32 v[148:149], v[154:155], v[222:223], v[148:149] op_sel_hi:[0,1,1]
	ds_read_b128 v[218:221], v185 offset:7696
	ds_read_b64 v[234:235], v185 offset:7712
	ds_read2_b32 v[240:241], v227 offset0:0 offset1:16
	s_waitcnt lgkmcnt(7)
	v_pk_mul_f32 v[150:151], v[146:147], v[190:191]
	v_pk_fma_f32 v[150:151], v[148:149], v[198:199], v[150:151]
	v_pk_mul_f32 v[152:153], v[146:147], v[236:237]
	v_add_f32_e32 v154, v150, v151
	v_pk_fma_f32 v[152:153], v[148:149], v[238:239], v[152:153]
	v_pk_mul_f32 v[142:143], v[146:147], v[192:193]
	v_add_f32_dpp v154, v154, v154 quad_perm:[1,0,3,2] row_mask:0xf bank_mask:0xf bound_ctrl:1
	v_pk_mul_f32 v[144:145], v[148:149], v[200:201]
	v_add_f32_e32 v170, v152, v153
	v_add_f32_dpp v154, v154, v154 quad_perm:[2,3,0,1] row_mask:0xf bank_mask:0xf bound_ctrl:1
	v_pk_fma_f32 v[142:143], v[242:243], v[196:197], v[142:143] op_sel:[1,0,0] op_sel_hi:[1,1,1]
	v_pk_fma_f32 v[144:145], v[242:243], v[204:205], v[144:145] op_sel:[1,0,0] op_sel_hi:[1,1,1]
	v_add_f32_dpp v154, v154, v154 row_half_mirror row_mask:0xf bank_mask:0xf bound_ctrl:1
	ds_read_b128 v[126:129], v184 offset:9216
	ds_read_b128 v[130:133], v184 offset:9232
	v_add_f32_dpp v154, v154, v154 row_mirror row_mask:0xf bank_mask:0xf bound_ctrl:1
	ds_read_b64 v[236:237], v184 offset:9248
	v_pk_fma_f32 v[142:143], v[154:155], v[194:195], v[142:143] op_sel_hi:[0,1,1]
	v_pk_fma_f32 v[144:145], v[154:155], v[202:203], v[144:145] op_sel_hi:[0,1,1]
	ds_read_b128 v[134:137], v185 offset:9216
	ds_read_b128 v[222:225], v185 offset:9232
	ds_read_b64 v[238:239], v185 offset:9248
	s_waitcnt lgkmcnt(6)
; __device__ __forceinline__ void wkv_phase(const WkvT& W, unsigned char* lds) {
;     ...
;                 const float* pp = sP + bo + jj * 12;
;                 const float* pv = sV + bi * 512 + il;
;                 f32x4 nA = *(const f32x4*)pp, nB = *(const f32x4*)(pp + 4); f32x2 nr = *(const f32x2*)(pp + 8); float nv = pv[0];
;                 float yk0 = 0.f, yk1 = 0.f, ep = 0.f;
;                 const bool oddrow = (lane & 16) != 0;
; #pragma unroll
;                 for (int t = 0; t < 32; ++t) {
;                     const f32x2 a2 = {nA[0], nA[1]}, w2 = {nA[2], nA[3]}, b2 = {nB[0], nB[1]}, k2 = {nB[2], nB[3]}, r2 = nr; const float v = nv;
;                     if (t + 1 < 32) { nA = *(const f32x4*)(pp + (t + 1) * 384); nB = *(const f32x4*)(pp + (t + 1) * 384 + 4); nr = *(const f32x2*)(pp + (t + 1) * 384 + 8); nv = pv[(t + 1) * 16]; }
;                     float S0 = S.x, S1 = S.y;
;                     float d = S0 * a2.x; d = __builtin_fmaf(S1, a2.y, d);
;                     float t0 = S0 * w2.x; t0 = __builtin_fmaf(v, k2.x, t0); asm volatile("" : "+v"(t0));
;                     float t1 = S1 * w2.y; t1 = __builtin_fmaf(v, k2.y, t1); asm volatile("" : "+v"(t1));
;                     float yprev; const float sa = wkv_reduce(d, ep, yprev);
;                     S0 = __builtin_fmaf(sa, b2.x, t0); asm volatile("" : "+v"(S0));
;                     S1 = __builtin_fmaf(sa, b2.y, t1); asm volatile("" : "+v"(S1));
;                     ep = S0 * r2.x; ep = __builtin_fmaf(S1, r2.y, ep);
;                     S.x = S0; S.y = S1;
;                     if (t >= 1) { const bool hit = oddrow && ((lane & 15) == ((t - 1) & 15)); if (t <= 16) yk0 = hit ? yprev : yk0; else yk1 = hit ? yprev : yk1; }
;                 }
;                 { float ylast; (void)wkv_reduce(0.f, ep, ylast); yk1 = (oddrow && (lane & 15) == 15) ? ylast : yk1; }
;                 if (oddrow) { sY[bi * 512 + (lane & 15) * 16 + il] = yk0; sY[bi * 512 + (16 + (lane & 15)) * 16 + il] = yk1; }
	v_pk_mul_f32 v[150:151], v[142:143], v[206:207]
	v_pk_fma_f32 v[150:151], v[144:145], v[214:215], v[150:151]
	v_pk_mul_f32 v[152:153], v[142:143], v[228:229]
	v_add_f32_e32 v154, v150, v151
	v_pk_fma_f32 v[152:153], v[144:145], v[230:231], v[152:153]
	v_pk_mul_f32 v[146:147], v[142:143], v[208:209]
	v_add_f32_dpp v154, v154, v154 quad_perm:[1,0,3,2] row_mask:0xf bank_mask:0xf bound_ctrl:1
	v_pk_mul_f32 v[148:149], v[144:145], v[216:217]
	v_add_f32_e32 v171, v152, v153
	v_add_f32_dpp v154, v154, v154 quad_perm:[2,3,0,1] row_mask:0xf bank_mask:0xf bound_ctrl:1
	v_pk_fma_f32 v[146:147], v[240:241], v[212:213], v[146:147] op_sel:[0,0,0] op_sel_hi:[0,1,1]
	v_pk_fma_f32 v[148:149], v[240:241], v[220:221], v[148:149] op_sel:[0,0,0] op_sel_hi:[0,1,1]
	v_add_f32_dpp v154, v154, v154 row_half_mirror row_mask:0xf bank_mask:0xf bound_ctrl:1
	ds_read_b128 v[190:193], v184 offset:10752
	ds_read_b128 v[194:197], v184 offset:10768
	v_add_f32_dpp v154, v154, v154 row_mirror row_mask:0xf bank_mask:0xf bound_ctrl:1
	ds_read_b64 v[228:229], v184 offset:10784
	ds_read_b128 v[198:201], v185 offset:10752
	v_pk_fma_f32 v[146:147], v[154:155], v[210:211], v[146:147] op_sel_hi:[0,1,1]
	v_pk_fma_f32 v[148:149], v[154:155], v[218:219], v[148:149] op_sel_hi:[0,1,1]
	ds_read_b128 v[202:205], v185 offset:10768
	ds_read_b64 v[230:231], v185 offset:10784
	ds_read2_b32 v[242:243], v227 offset0:32 offset1:48
	s_waitcnt lgkmcnt(7)
	v_add_f32_dpp v172, v156, v156 row_ror:8 row_mask:0xf bank_mask:0x3
	v_add_f32_dpp v172, v164, v164 row_ror:8 row_mask:0xf bank_mask:0xc
	v_add_f32_dpp v173, v157, v157 row_ror:8 row_mask:0xf bank_mask:0x3
	v_add_f32_dpp v173, v165, v165 row_ror:8 row_mask:0xf bank_mask:0xc
	v_add_f32_dpp v174, v158, v158 row_ror:8 row_mask:0xf bank_mask:0x3
	v_add_f32_dpp v174, v166, v166 row_ror:8 row_mask:0xf bank_mask:0xc
	v_add_f32_dpp v175, v159, v159 row_ror:8 row_mask:0xf bank_mask:0x3
	v_add_f32_dpp v175, v167, v167 row_ror:8 row_mask:0xf bank_mask:0xc
	v_add_f32_dpp v176, v160, v160 row_ror:8 row_mask:0xf bank_mask:0x3
	v_add_f32_dpp v176, v168, v168 row_ror:8 row_mask:0xf bank_mask:0xc
	v_add_f32_dpp v177, v161, v161 row_ror:8 row_mask:0xf bank_mask:0x3
	v_add_f32_dpp v177, v169, v169 row_ror:8 row_mask:0xf bank_mask:0xc
	v_add_f32_dpp v178, v162, v162 row_ror:8 row_mask:0xf bank_mask:0x3
	v_add_f32_dpp v178, v170, v170 row_ror:8 row_mask:0xf bank_mask:0xc
	v_add_f32_dpp v179, v163, v163 row_ror:8 row_mask:0xf bank_mask:0x3
	v_add_f32_dpp v179, v171, v171 row_ror:8 row_mask:0xf bank_mask:0xc
	v_add_f32_dpp v156, v172, v172 row_half_mirror row_mask:0xf bank_mask:0x5
	v_add_f32_dpp v156, v176, v176 row_half_mirror row_mask:0xf bank_mask:0xa
	v_add_f32_dpp v157, v173, v173 row_half_mirror row_mask:0xf bank_mask:0x5
	v_add_f32_dpp v157, v177, v177 row_half_mirror row_mask:0xf bank_mask:0xa
	v_add_f32_dpp v158, v174, v174 row_half_mirror row_mask:0xf bank_mask:0x5
	v_add_f32_dpp v158, v178, v178 row_half_mirror row_mask:0xf bank_mask:0xa
	v_add_f32_dpp v159, v175, v175 row_half_mirror row_mask:0xf bank_mask:0x5
	v_add_f32_dpp v159, v179, v179 row_half_mirror row_mask:0xf bank_mask:0xa
	v_cndmask_b32_e64 v176, v158, v156, s[14:15]
	v_cndmask_b32_e64 v177, v159, v157, s[14:15]
	v_cndmask_b32_e64 v178, v156, v158, s[14:15]
	v_cndmask_b32_e64 v179, v157, v159, s[14:15]
	v_add_f32_dpp v172, v176, v178 quad_perm:[2,3,0,1] row_mask:0xf bank_mask:0xf
	v_add_f32_dpp v173, v177, v179 quad_perm:[2,3,0,1] row_mask:0xf bank_mask:0xf
	v_cndmask_b32_e64 v176, v173, v172, s[16:17]
	v_cndmask_b32_e64 v178, v172, v173, s[16:17]
	s_nop 0
	v_add_f32_dpp v180, v176, v178 quad_perm:[1,0,3,2] row_mask:0xf bank_mask:0xf
	v_pk_mul_f32 v[150:151], v[146:147], v[126:127]
	v_pk_fma_f32 v[150:151], v[148:149], v[134:135], v[150:151]
	v_pk_mul_f32 v[152:153], v[146:147], v[232:233]
	v_add_f32_e32 v154, v150, v151
	v_pk_fma_f32 v[152:153], v[148:149], v[234:235], v[152:153]
	v_pk_mul_f32 v[142:143], v[146:147], v[128:129]
	v_add_f32_dpp v154, v154, v154 quad_perm:[1,0,3,2] row_mask:0xf bank_mask:0xf bound_ctrl:1
	v_pk_mul_f32 v[144:145], v[148:149], v[136:137]
	v_add_f32_e32 v156, v152, v153
	v_add_f32_dpp v154, v154, v154 quad_perm:[2,3,0,1] row_mask:0xf bank_mask:0xf bound_ctrl:1
	v_pk_fma_f32 v[142:143], v[240:241], v[132:133], v[142:143] op_sel:[1,0,0] op_sel_hi:[1,1,1]
	v_pk_fma_f32 v[144:145], v[240:241], v[224:225], v[144:145] op_sel:[1,0,0] op_sel_hi:[1,1,1]
	v_add_f32_dpp v154, v154, v154 row_half_mirror row_mask:0xf bank_mask:0xf bound_ctrl:1
	ds_read_b128 v[206:209], v184 offset:12288
	ds_read_b128 v[210:213], v184 offset:12304
	v_add_f32_dpp v154, v154, v154 row_mirror row_mask:0xf bank_mask:0xf bound_ctrl:1
	ds_read_b64 v[232:233], v184 offset:12320
	v_pk_fma_f32 v[142:143], v[154:155], v[130:131], v[142:143] op_sel_hi:[0,1,1]
	v_pk_fma_f32 v[144:145], v[154:155], v[222:223], v[144:145] op_sel_hi:[0,1,1]
	ds_read_b128 v[214:217], v185 offset:12288
	ds_read_b128 v[218:221], v185 offset:12304
	ds_read_b64 v[234:235], v185 offset:12320
	s_waitcnt lgkmcnt(6)
; __device__ __forceinline__ void wkv_phase(const WkvT& W, unsigned char* lds) {
;     ...
;                 const float* pp = sP + bo + jj * 12;
;                 const float* pv = sV + bi * 512 + il;
;                 f32x4 nA = *(const f32x4*)pp, nB = *(const f32x4*)(pp + 4); f32x2 nr = *(const f32x2*)(pp + 8); float nv = pv[0];
;                 float yk0 = 0.f, yk1 = 0.f, ep = 0.f;
;                 const bool oddrow = (lane & 16) != 0;
; #pragma unroll
;                 for (int t = 0; t < 32; ++t) {
;                     const f32x2 a2 = {nA[0], nA[1]}, w2 = {nA[2], nA[3]}, b2 = {nB[0], nB[1]}, k2 = {nB[2], nB[3]}, r2 = nr; const float v = nv;
;                     if (t + 1 < 32) { nA = *(const f32x4*)(pp + (t + 1) * 384); nB = *(const f32x4*)(pp + (t + 1) * 384 + 4); nr = *(const f32x2*)(pp + (t + 1) * 384 + 8); nv = pv[(t + 1) * 16]; }
;                     float S0 = S.x, S1 = S.y;
;                     float d = S0 * a2.x; d = __builtin_fmaf(S1, a2.y, d);
;                     float t0 = S0 * w2.x; t0 = __builtin_fmaf(v, k2.x, t0); asm volatile("" : "+v"(t0));
;                     float t1 = S1 * w2.y; t1 = __builtin_fmaf(v, k2.y, t1); asm volatile("" : "+v"(t1));
;                     float yprev; const float sa = wkv_reduce(d, ep, yprev);
;                     S0 = __builtin_fmaf(sa, b2.x, t0); asm volatile("" : "+v"(S0));
;                     S1 = __builtin_fmaf(sa, b2.y, t1); asm volatile("" : "+v"(S1));
;                     ep = S0 * r2.x; ep = __builtin_fmaf(S1, r2.y, ep);
;                     S.x = S0; S.y = S1;
	v_pk_mul_f32 v[150:151], v[142:143], v[190:191]
	v_pk_fma_f32 v[150:151], v[144:145], v[198:199], v[150:151]
	v_pk_mul_f32 v[152:153], v[142:143], v[236:237]
	v_add_f32_e32 v154, v150, v151
	v_pk_fma_f32 v[152:153], v[144:145], v[238:239], v[152:153]
	v_pk_mul_f32 v[146:147], v[142:143], v[192:193]
	v_add_f32_dpp v154, v154, v154 quad_perm:[1,0,3,2] row_mask:0xf bank_mask:0xf bound_ctrl:1
	v_pk_mul_f32 v[148:149], v[144:145], v[200:201]
	v_add_f32_e32 v157, v152, v153
	v_add_f32_dpp v154, v154, v154 quad_perm:[2,3,0,1] row_mask:0xf bank_mask:0xf bound_ctrl:1
	v_pk_fma_f32 v[146:147], v[242:243], v[196:197], v[146:147] op_sel:[0,0,0] op_sel_hi:[0,1,1]
	v_pk_fma_f32 v[148:149], v[242:243], v[204:205], v[148:149] op_sel:[0,0,0] op_sel_hi:[0,1,1]
	v_add_f32_dpp v154, v154, v154 row_half_mirror row_mask:0xf bank_mask:0xf bound_ctrl:1
	ds_read_b128 v[126:129], v184 offset:13824
	ds_read_b128 v[130:133], v184 offset:13840
	v_add_f32_dpp v154, v154, v154 row_mirror row_mask:0xf bank_mask:0xf bound_ctrl:1
	ds_read_b64 v[236:237], v184 offset:13856
	ds_read_b128 v[134:137], v185 offset:13824
	v_pk_fma_f32 v[146:147], v[154:155], v[194:195], v[146:147] op_sel_hi:[0,1,1]
	v_pk_fma_f32 v[148:149], v[154:155], v[202:203], v[148:149] op_sel_hi:[0,1,1]
	ds_read_b128 v[222:225], v185 offset:13840
	ds_read_b64 v[238:239], v185 offset:13856
	ds_read2_b32 v[240:241], v227 offset0:64 offset1:80
	s_waitcnt lgkmcnt(7)
	v_pk_mul_f32 v[150:151], v[146:147], v[206:207]
	v_pk_fma_f32 v[150:151], v[148:149], v[214:215], v[150:151]
	v_pk_mul_f32 v[152:153], v[146:147], v[228:229]
	v_add_f32_e32 v154, v150, v151
	v_pk_fma_f32 v[152:153], v[148:149], v[230:231], v[152:153]
	v_pk_mul_f32 v[142:143], v[146:147], v[208:209]
	v_add_f32_dpp v154, v154, v154 quad_perm:[1,0,3,2] row_mask:0xf bank_mask:0xf bound_ctrl:1
	v_pk_mul_f32 v[144:145], v[148:149], v[216:217]
	v_add_f32_e32 v158, v152, v153
	v_add_f32_dpp v154, v154, v154 quad_perm:[2,3,0,1] row_mask:0xf bank_mask:0xf bound_ctrl:1
	v_pk_fma_f32 v[142:143], v[242:243], v[212:213], v[142:143] op_sel:[1,0,0] op_sel_hi:[1,1,1]
	v_pk_fma_f32 v[144:145], v[242:243], v[220:221], v[144:145] op_sel:[1,0,0] op_sel_hi:[1,1,1]
	v_add_f32_dpp v154, v154, v154 row_half_mirror row_mask:0xf bank_mask:0xf bound_ctrl:1
	ds_read_b128 v[190:193], v184 offset:15360
	ds_read_b128 v[194:197], v184 offset:15376
	v_add_f32_dpp v154, v154, v154 row_mirror row_mask:0xf bank_mask:0xf bound_ctrl:1
	ds_read_b64 v[228:229], v184 offset:15392
	v_pk_fma_f32 v[142:143], v[154:155], v[210:211], v[142:143] op_sel_hi:[0,1,1]
	v_pk_fma_f32 v[144:145], v[154:155], v[218:219], v[144:145] op_sel_hi:[0,1,1]
	ds_read_b128 v[198:201], v185 offset:15360
	ds_read_b128 v[202:205], v185 offset:15376
	ds_read_b64 v[230:231], v185 offset:15392
	s_waitcnt lgkmcnt(6)
	v_pk_mul_f32 v[150:151], v[142:143], v[126:127]
	v_pk_fma_f32 v[150:151], v[144:145], v[134:135], v[150:151]
	v_pk_mul_f32 v[152:153], v[142:143], v[232:233]
	v_add_f32_e32 v154, v150, v151
	v_pk_fma_f32 v[152:153], v[144:145], v[234:235], v[152:153]
	v_pk_mul_f32 v[146:147], v[142:143], v[128:129]
	v_add_f32_dpp v154, v154, v154 quad_perm:[1,0,3,2] row_mask:0xf bank_mask:0xf bound_ctrl:1
	v_pk_mul_f32 v[148:149], v[144:145], v[136:137]
	v_add_f32_e32 v159, v152, v153
	v_add_f32_dpp v154, v154, v154 quad_perm:[2,3,0,1] row_mask:0xf bank_mask:0xf bound_ctrl:1
	v_pk_fma_f32 v[146:147], v[240:241], v[132:133], v[146:147] op_sel:[0,0,0] op_sel_hi:[0,1,1]
	v_pk_fma_f32 v[148:149], v[240:241], v[224:225], v[148:149] op_sel:[0,0,0] op_sel_hi:[0,1,1]
	v_add_f32_dpp v154, v154, v154 row_half_mirror row_mask:0xf bank_mask:0xf bound_ctrl:1
	ds_read_b128 v[206:209], v184 offset:16896
	ds_read_b128 v[210:213], v184 offset:16912
	v_add_f32_dpp v154, v154, v154 row_mirror row_mask:0xf bank_mask:0xf bound_ctrl:1
	ds_read_b64 v[232:233], v184 offset:16928
	ds_read_b128 v[214:217], v185 offset:16896
	v_pk_fma_f32 v[146:147], v[154:155], v[130:131], v[146:147] op_sel_hi:[0,1,1]
	v_pk_fma_f32 v[148:149], v[154:155], v[222:223], v[148:149] op_sel_hi:[0,1,1]
	ds_read_b128 v[218:221], v185 offset:16912
	ds_read_b64 v[234:235], v185 offset:16928
	ds_read2_b32 v[242:243], v227 offset0:96 offset1:112
	s_waitcnt lgkmcnt(7)
	v_pk_mul_f32 v[150:151], v[146:147], v[190:191]
	v_pk_fma_f32 v[150:151], v[148:149], v[198:199], v[150:151]
	v_pk_mul_f32 v[152:153], v[146:147], v[236:237]
	v_add_f32_e32 v154, v150, v151
	v_pk_fma_f32 v[152:153], v[148:149], v[238:239], v[152:153]
	v_pk_mul_f32 v[142:143], v[146:147], v[192:193]
	v_add_f32_dpp v154, v154, v154 quad_perm:[1,0,3,2] row_mask:0xf bank_mask:0xf bound_ctrl:1
	v_pk_mul_f32 v[144:145], v[148:149], v[200:201]
	v_add_f32_e32 v160, v152, v153
	v_add_f32_dpp v154, v154, v154 quad_perm:[2,3,0,1] row_mask:0xf bank_mask:0xf bound_ctrl:1
	v_pk_fma_f32 v[142:143], v[240:241], v[196:197], v[142:143] op_sel:[1,0,0] op_sel_hi:[1,1,1]
	v_pk_fma_f32 v[144:145], v[240:241], v[204:205], v[144:145] op_sel:[1,0,0] op_sel_hi:[1,1,1]
	v_add_f32_dpp v154, v154, v154 row_half_mirror row_mask:0xf bank_mask:0xf bound_ctrl:1
	ds_read_b128 v[126:129], v184 offset:18432
	ds_read_b128 v[130:133], v184 offset:18448
	v_add_f32_dpp v154, v154, v154 row_mirror row_mask:0xf bank_mask:0xf bound_ctrl:1
	ds_read_b64 v[236:237], v184 offset:18464
	v_pk_fma_f32 v[142:143], v[154:155], v[194:195], v[142:143] op_sel_hi:[0,1,1]
	v_pk_fma_f32 v[144:145], v[154:155], v[202:203], v[144:145] op_sel_hi:[0,1,1]
	ds_read_b128 v[134:137], v185 offset:18432
	ds_read_b128 v[222:225], v185 offset:18448
	ds_read_b64 v[238:239], v185 offset:18464
	s_waitcnt lgkmcnt(6)
; __device__ __forceinline__ void wkv_phase(const WkvT& W, unsigned char* lds) {
;     ...
;                 const float* pp = sP + bo + jj * 12;
;                 const float* pv = sV + bi * 512 + il;
;                 f32x4 nA = *(const f32x4*)pp, nB = *(const f32x4*)(pp + 4); f32x2 nr = *(const f32x2*)(pp + 8); float nv = pv[0];
;                 float yk0 = 0.f, yk1 = 0.f, ep = 0.f;
;                 const bool oddrow = (lane & 16) != 0;
; #pragma unroll
;                 for (int t = 0; t < 32; ++t) {
;                     const f32x2 a2 = {nA[0], nA[1]}, w2 = {nA[2], nA[3]}, b2 = {nB[0], nB[1]}, k2 = {nB[2], nB[3]}, r2 = nr; const float v = nv;
;                     if (t + 1 < 32) { nA = *(const f32x4*)(pp + (t + 1) * 384); nB = *(const f32x4*)(pp + (t + 1) * 384 + 4); nr = *(const f32x2*)(pp + (t + 1) * 384 + 8); nv = pv[(t + 1) * 16]; }
;                     float S0 = S.x, S1 = S.y;
;                     float d = S0 * a2.x; d = __builtin_fmaf(S1, a2.y, d);
;                     float t0 = S0 * w2.x; t0 = __builtin_fmaf(v, k2.x, t0); asm volatile("" : "+v"(t0));
;                     float t1 = S1 * w2.y; t1 = __builtin_fmaf(v, k2.y, t1); asm volatile("" : "+v"(t1));
;                     float yprev; const float sa = wkv_reduce(d, ep, yprev);
;                     S0 = __builtin_fmaf(sa, b2.x, t0); asm volatile("" : "+v"(S0));
;                     S1 = __builtin_fmaf(sa, b2.y, t1); asm volatile("" : "+v"(S1));
;                     ep = S0 * r2.x; ep = __builtin_fmaf(S1, r2.y, ep);
;                     S.x = S0; S.y = S1;
	v_pk_mul_f32 v[150:151], v[142:143], v[206:207]
	v_pk_fma_f32 v[150:151], v[144:145], v[214:215], v[150:151]
	v_pk_mul_f32 v[152:153], v[142:143], v[228:229]
	v_add_f32_e32 v154, v150, v151
	v_pk_fma_f32 v[152:153], v[144:145], v[230:231], v[152:153]
	v_pk_mul_f32 v[146:147], v[142:143], v[208:209]
	v_add_f32_dpp v154, v154, v154 quad_perm:[1,0,3,2] row_mask:0xf bank_mask:0xf bound_ctrl:1
	v_pk_mul_f32 v[148:149], v[144:145], v[216:217]
	v_add_f32_e32 v161, v152, v153
	v_add_f32_dpp v154, v154, v154 quad_perm:[2,3,0,1] row_mask:0xf bank_mask:0xf bound_ctrl:1
	v_pk_fma_f32 v[146:147], v[242:243], v[212:213], v[146:147] op_sel:[0,0,0] op_sel_hi:[0,1,1]
	v_pk_fma_f32 v[148:149], v[242:243], v[220:221], v[148:149] op_sel:[0,0,0] op_sel_hi:[0,1,1]
	v_add_f32_dpp v154, v154, v154 row_half_mirror row_mask:0xf bank_mask:0xf bound_ctrl:1
	ds_read_b128 v[190:193], v184 offset:19968
	ds_read_b128 v[194:197], v184 offset:19984
	v_add_f32_dpp v154, v154, v154 row_mirror row_mask:0xf bank_mask:0xf bound_ctrl:1
	ds_read_b64 v[228:229], v184 offset:20000
	ds_read_b128 v[198:201], v185 offset:19968
	v_pk_fma_f32 v[146:147], v[154:155], v[210:211], v[146:147] op_sel_hi:[0,1,1]
	v_pk_fma_f32 v[148:149], v[154:155], v[218:219], v[148:149] op_sel_hi:[0,1,1]
	ds_read_b128 v[202:205], v185 offset:19984
	ds_read_b64 v[230:231], v185 offset:20000
	ds_read2_b32 v[240:241], v227 offset0:128 offset1:144
	s_waitcnt lgkmcnt(7)
	v_pk_mul_f32 v[150:151], v[146:147], v[126:127]
	v_pk_fma_f32 v[150:151], v[148:149], v[134:135], v[150:151]
	v_pk_mul_f32 v[152:153], v[146:147], v[232:233]
	v_add_f32_e32 v154, v150, v151
	v_pk_fma_f32 v[152:153], v[148:149], v[234:235], v[152:153]
	v_pk_mul_f32 v[142:143], v[146:147], v[128:129]
	v_add_f32_dpp v154, v154, v154 quad_perm:[1,0,3,2] row_mask:0xf bank_mask:0xf bound_ctrl:1
	v_pk_mul_f32 v[144:145], v[148:149], v[136:137]
	v_add_f32_e32 v162, v152, v153
	v_add_f32_dpp v154, v154, v154 quad_perm:[2,3,0,1] row_mask:0xf bank_mask:0xf bound_ctrl:1
	v_pk_fma_f32 v[142:143], v[242:243], v[132:133], v[142:143] op_sel:[1,0,0] op_sel_hi:[1,1,1]
	v_pk_fma_f32 v[144:145], v[242:243], v[224:225], v[144:145] op_sel:[1,0,0] op_sel_hi:[1,1,1]
	v_add_f32_dpp v154, v154, v154 row_half_mirror row_mask:0xf bank_mask:0xf bound_ctrl:1
	ds_read_b128 v[206:209], v184 offset:21504
	ds_read_b128 v[210:213], v184 offset:21520
	v_add_f32_dpp v154, v154, v154 row_mirror row_mask:0xf bank_mask:0xf bound_ctrl:1
	ds_read_b64 v[232:233], v184 offset:21536
	v_pk_fma_f32 v[142:143], v[154:155], v[130:131], v[142:143] op_sel_hi:[0,1,1]
	v_pk_fma_f32 v[144:145], v[154:155], v[222:223], v[144:145] op_sel_hi:[0,1,1]
	ds_read_b128 v[214:217], v185 offset:21504
	ds_read_b128 v[218:221], v185 offset:21520
	ds_read_b64 v[234:235], v185 offset:21536
	s_waitcnt lgkmcnt(6)
	v_pk_mul_f32 v[150:151], v[142:143], v[190:191]
	v_pk_fma_f32 v[150:151], v[144:145], v[198:199], v[150:151]
	v_pk_mul_f32 v[152:153], v[142:143], v[236:237]
	v_add_f32_e32 v154, v150, v151
	v_pk_fma_f32 v[152:153], v[144:145], v[238:239], v[152:153]
	v_pk_mul_f32 v[146:147], v[142:143], v[192:193]
	v_add_f32_dpp v154, v154, v154 quad_perm:[1,0,3,2] row_mask:0xf bank_mask:0xf bound_ctrl:1
	v_pk_mul_f32 v[148:149], v[144:145], v[200:201]
	v_add_f32_e32 v163, v152, v153
	v_add_f32_dpp v154, v154, v154 quad_perm:[2,3,0,1] row_mask:0xf bank_mask:0xf bound_ctrl:1
	v_pk_fma_f32 v[146:147], v[240:241], v[196:197], v[146:147] op_sel:[0,0,0] op_sel_hi:[0,1,1]
	v_pk_fma_f32 v[148:149], v[240:241], v[204:205], v[148:149] op_sel:[0,0,0] op_sel_hi:[0,1,1]
	v_add_f32_dpp v154, v154, v154 row_half_mirror row_mask:0xf bank_mask:0xf bound_ctrl:1
	ds_read_b128 v[126:129], v184 offset:23040
	ds_read_b128 v[130:133], v184 offset:23056
	v_add_f32_dpp v154, v154, v154 row_mirror row_mask:0xf bank_mask:0xf bound_ctrl:1
	ds_read_b64 v[236:237], v184 offset:23072
	ds_read_b128 v[134:137], v185 offset:23040
	v_pk_fma_f32 v[146:147], v[154:155], v[194:195], v[146:147] op_sel_hi:[0,1,1]
	v_pk_fma_f32 v[148:149], v[154:155], v[202:203], v[148:149] op_sel_hi:[0,1,1]
	ds_read_b128 v[222:225], v185 offset:23056
	ds_read_b64 v[238:239], v185 offset:23072
	ds_read2_b32 v[242:243], v227 offset0:160 offset1:176
	s_waitcnt lgkmcnt(7)
	v_pk_mul_f32 v[150:151], v[146:147], v[206:207]
	v_pk_fma_f32 v[150:151], v[148:149], v[214:215], v[150:151]
	v_pk_mul_f32 v[152:153], v[146:147], v[228:229]
	v_add_f32_e32 v154, v150, v151
	v_pk_fma_f32 v[152:153], v[148:149], v[230:231], v[152:153]
	v_pk_mul_f32 v[142:143], v[146:147], v[208:209]
	v_add_f32_dpp v154, v154, v154 quad_perm:[1,0,3,2] row_mask:0xf bank_mask:0xf bound_ctrl:1
	v_pk_mul_f32 v[144:145], v[148:149], v[216:217]
	v_add_f32_e32 v164, v152, v153
	v_add_f32_dpp v154, v154, v154 quad_perm:[2,3,0,1] row_mask:0xf bank_mask:0xf bound_ctrl:1
	v_pk_fma_f32 v[142:143], v[240:241], v[212:213], v[142:143] op_sel:[1,0,0] op_sel_hi:[1,1,1]
	v_pk_fma_f32 v[144:145], v[240:241], v[220:221], v[144:145] op_sel:[1,0,0] op_sel_hi:[1,1,1]
	v_add_f32_dpp v154, v154, v154 row_half_mirror row_mask:0xf bank_mask:0xf bound_ctrl:1
	ds_read_b128 v[190:193], v184 offset:24576
	ds_read_b128 v[194:197], v184 offset:24592
	v_add_f32_dpp v154, v154, v154 row_mirror row_mask:0xf bank_mask:0xf bound_ctrl:1
	ds_read_b64 v[228:229], v184 offset:24608
	v_pk_fma_f32 v[142:143], v[154:155], v[210:211], v[142:143] op_sel_hi:[0,1,1]
	v_pk_fma_f32 v[144:145], v[154:155], v[218:219], v[144:145] op_sel_hi:[0,1,1]
	ds_read_b128 v[198:201], v185 offset:24576
	ds_read_b128 v[202:205], v185 offset:24592
	ds_read_b64 v[230:231], v185 offset:24608
	s_waitcnt lgkmcnt(6)
; __device__ __forceinline__ void wkv_phase(const WkvT& W, unsigned char* lds) {
;     ...
;                 const float* pp = sP + bo + jj * 12;
;                 const float* pv = sV + bi * 512 + il;
;                 f32x4 nA = *(const f32x4*)pp, nB = *(const f32x4*)(pp + 4); f32x2 nr = *(const f32x2*)(pp + 8); float nv = pv[0];
;                 float yk0 = 0.f, yk1 = 0.f, ep = 0.f;
;                 const bool oddrow = (lane & 16) != 0;
; #pragma unroll
;                 for (int t = 0; t < 32; ++t) {
;                     const f32x2 a2 = {nA[0], nA[1]}, w2 = {nA[2], nA[3]}, b2 = {nB[0], nB[1]}, k2 = {nB[2], nB[3]}, r2 = nr; const float v = nv;
;                     if (t + 1 < 32) { nA = *(const f32x4*)(pp + (t + 1) * 384); nB = *(const f32x4*)(pp + (t + 1) * 384 + 4); nr = *(const f32x2*)(pp + (t + 1) * 384 + 8); nv = pv[(t + 1) * 16]; }
;                     float S0 = S.x, S1 = S.y;
;                     float d = S0 * a2.x; d = __builtin_fmaf(S1, a2.y, d);
;                     float t0 = S0 * w2.x; t0 = __builtin_fmaf(v, k2.x, t0); asm volatile("" : "+v"(t0));
;                     float t1 = S1 * w2.y; t1 = __builtin_fmaf(v, k2.y, t1); asm volatile("" : "+v"(t1));
;                     float yprev; const float sa = wkv_reduce(d, ep, yprev);
;                     S0 = __builtin_fmaf(sa, b2.x, t0); asm volatile("" : "+v"(S0));
;                     S1 = __builtin_fmaf(sa, b2.y, t1); asm volatile("" : "+v"(S1));
;                     ep = S0 * r2.x; ep = __builtin_fmaf(S1, r2.y, ep);
;                     S.x = S0; S.y = S1;
	v_pk_mul_f32 v[150:151], v[142:143], v[126:127]
	v_pk_fma_f32 v[150:151], v[144:145], v[134:135], v[150:151]
	v_pk_mul_f32 v[152:153], v[142:143], v[232:233]
	v_add_f32_e32 v154, v150, v151
	v_pk_fma_f32 v[152:153], v[144:145], v[234:235], v[152:153]
	v_pk_mul_f32 v[146:147], v[142:143], v[128:129]
	v_add_f32_dpp v154, v154, v154 quad_perm:[1,0,3,2] row_mask:0xf bank_mask:0xf bound_ctrl:1
	v_pk_mul_f32 v[148:149], v[144:145], v[136:137]
	v_add_f32_e32 v165, v152, v153
	v_add_f32_dpp v154, v154, v154 quad_perm:[2,3,0,1] row_mask:0xf bank_mask:0xf bound_ctrl:1
	v_pk_fma_f32 v[146:147], v[242:243], v[132:133], v[146:147] op_sel:[0,0,0] op_sel_hi:[0,1,1]
	v_pk_fma_f32 v[148:149], v[242:243], v[224:225], v[148:149] op_sel:[0,0,0] op_sel_hi:[0,1,1]
	v_add_f32_dpp v154, v154, v154 row_half_mirror row_mask:0xf bank_mask:0xf bound_ctrl:1
	ds_read_b128 v[206:209], v184 offset:26112
	ds_read_b128 v[210:213], v184 offset:26128
	v_add_f32_dpp v154, v154, v154 row_mirror row_mask:0xf bank_mask:0xf bound_ctrl:1
	ds_read_b64 v[232:233], v184 offset:26144
	ds_read_b128 v[214:217], v185 offset:26112
	v_pk_fma_f32 v[146:147], v[154:155], v[130:131], v[146:147] op_sel_hi:[0,1,1]
	v_pk_fma_f32 v[148:149], v[154:155], v[222:223], v[148:149] op_sel_hi:[0,1,1]
	ds_read_b128 v[218:221], v185 offset:26128
	ds_read_b64 v[234:235], v185 offset:26144
	ds_read2_b32 v[240:241], v227 offset0:192 offset1:208
	s_waitcnt lgkmcnt(7)
	v_pk_mul_f32 v[150:151], v[146:147], v[190:191]
	v_pk_fma_f32 v[150:151], v[148:149], v[198:199], v[150:151]
	v_pk_mul_f32 v[152:153], v[146:147], v[236:237]
	v_add_f32_e32 v154, v150, v151
	v_pk_fma_f32 v[152:153], v[148:149], v[238:239], v[152:153]
	v_pk_mul_f32 v[142:143], v[146:147], v[192:193]
	v_add_f32_dpp v154, v154, v154 quad_perm:[1,0,3,2] row_mask:0xf bank_mask:0xf bound_ctrl:1
	v_pk_mul_f32 v[144:145], v[148:149], v[200:201]
	v_add_f32_e32 v166, v152, v153
	v_add_f32_dpp v154, v154, v154 quad_perm:[2,3,0,1] row_mask:0xf bank_mask:0xf bound_ctrl:1
	v_pk_fma_f32 v[142:143], v[242:243], v[196:197], v[142:143] op_sel:[1,0,0] op_sel_hi:[1,1,1]
	v_pk_fma_f32 v[144:145], v[242:243], v[204:205], v[144:145] op_sel:[1,0,0] op_sel_hi:[1,1,1]
	v_add_f32_dpp v154, v154, v154 row_half_mirror row_mask:0xf bank_mask:0xf bound_ctrl:1
	ds_read_b128 v[126:129], v184 offset:27648
	ds_read_b128 v[130:133], v184 offset:27664
	v_add_f32_dpp v154, v154, v154 row_mirror row_mask:0xf bank_mask:0xf bound_ctrl:1
	ds_read_b64 v[236:237], v184 offset:27680
	v_pk_fma_f32 v[142:143], v[154:155], v[194:195], v[142:143] op_sel_hi:[0,1,1]
	v_pk_fma_f32 v[144:145], v[154:155], v[202:203], v[144:145] op_sel_hi:[0,1,1]
	ds_read_b128 v[134:137], v185 offset:27648
	ds_read_b128 v[222:225], v185 offset:27664
	ds_read_b64 v[238:239], v185 offset:27680
	s_waitcnt lgkmcnt(6)
	v_pk_mul_f32 v[150:151], v[142:143], v[206:207]
	v_pk_fma_f32 v[150:151], v[144:145], v[214:215], v[150:151]
	v_pk_mul_f32 v[152:153], v[142:143], v[228:229]
	v_add_f32_e32 v154, v150, v151
	v_pk_fma_f32 v[152:153], v[144:145], v[230:231], v[152:153]
	v_pk_mul_f32 v[146:147], v[142:143], v[208:209]
	v_add_f32_dpp v154, v154, v154 quad_perm:[1,0,3,2] row_mask:0xf bank_mask:0xf bound_ctrl:1
	v_pk_mul_f32 v[148:149], v[144:145], v[216:217]
	v_add_f32_e32 v167, v152, v153
	v_add_f32_dpp v154, v154, v154 quad_perm:[2,3,0,1] row_mask:0xf bank_mask:0xf bound_ctrl:1
	v_pk_fma_f32 v[146:147], v[240:241], v[212:213], v[146:147] op_sel:[0,0,0] op_sel_hi:[0,1,1]
	v_pk_fma_f32 v[148:149], v[240:241], v[220:221], v[148:149] op_sel:[0,0,0] op_sel_hi:[0,1,1]
	v_add_f32_dpp v154, v154, v154 row_half_mirror row_mask:0xf bank_mask:0xf bound_ctrl:1
	ds_read_b128 v[190:193], v184 offset:29184
	ds_read_b128 v[194:197], v184 offset:29200
	v_add_f32_dpp v154, v154, v154 row_mirror row_mask:0xf bank_mask:0xf bound_ctrl:1
	ds_read_b64 v[228:229], v184 offset:29216
	ds_read_b128 v[198:201], v185 offset:29184
	v_pk_fma_f32 v[146:147], v[154:155], v[210:211], v[146:147] op_sel_hi:[0,1,1]
	v_pk_fma_f32 v[148:149], v[154:155], v[218:219], v[148:149] op_sel_hi:[0,1,1]
	ds_read_b128 v[202:205], v185 offset:29200
	ds_read_b64 v[230:231], v185 offset:29216
	ds_read2_b32 v[242:243], v227 offset0:224 offset1:240
	s_waitcnt lgkmcnt(7)
	v_pk_mul_f32 v[150:151], v[146:147], v[126:127]
	v_pk_fma_f32 v[150:151], v[148:149], v[134:135], v[150:151]
	v_pk_mul_f32 v[152:153], v[146:147], v[232:233]
	v_add_f32_e32 v154, v150, v151
	v_pk_fma_f32 v[152:153], v[148:149], v[234:235], v[152:153]
	v_pk_mul_f32 v[142:143], v[146:147], v[128:129]
	v_add_f32_dpp v154, v154, v154 quad_perm:[1,0,3,2] row_mask:0xf bank_mask:0xf bound_ctrl:1
	v_pk_mul_f32 v[144:145], v[148:149], v[136:137]
	v_add_f32_e32 v168, v152, v153
	v_add_f32_dpp v154, v154, v154 quad_perm:[2,3,0,1] row_mask:0xf bank_mask:0xf bound_ctrl:1
	v_pk_fma_f32 v[142:143], v[240:241], v[132:133], v[142:143] op_sel:[1,0,0] op_sel_hi:[1,1,1]
	v_pk_fma_f32 v[144:145], v[240:241], v[224:225], v[144:145] op_sel:[1,0,0] op_sel_hi:[1,1,1]
	v_add_f32_dpp v154, v154, v154 row_half_mirror row_mask:0xf bank_mask:0xf bound_ctrl:1
	ds_read_b128 v[206:209], v184 offset:30720
	ds_read_b128 v[210:213], v184 offset:30736
	v_add_f32_dpp v154, v154, v154 row_mirror row_mask:0xf bank_mask:0xf bound_ctrl:1
	ds_read_b64 v[232:233], v184 offset:30752
	v_pk_fma_f32 v[142:143], v[154:155], v[130:131], v[142:143] op_sel_hi:[0,1,1]
	v_pk_fma_f32 v[144:145], v[154:155], v[222:223], v[144:145] op_sel_hi:[0,1,1]
	ds_read_b128 v[214:217], v185 offset:30720
	ds_read_b128 v[218:221], v185 offset:30736
	ds_read_b64 v[234:235], v185 offset:30752
	s_waitcnt lgkmcnt(6)
; __device__ __forceinline__ void wkv_phase(const WkvT& W, unsigned char* lds) {
;     ...
;                 const float* pp = sP + bo + jj * 12;
;                 const float* pv = sV + bi * 512 + il;
;                 f32x4 nA = *(const f32x4*)pp, nB = *(const f32x4*)(pp + 4); f32x2 nr = *(const f32x2*)(pp + 8); float nv = pv[0];
;                 float yk0 = 0.f, yk1 = 0.f, ep = 0.f;
;                 const bool oddrow = (lane & 16) != 0;
; #pragma unroll
;                 for (int t = 0; t < 32; ++t) {
;                     const f32x2 a2 = {nA[0], nA[1]}, w2 = {nA[2], nA[3]}, b2 = {nB[0], nB[1]}, k2 = {nB[2], nB[3]}, r2 = nr; const float v = nv;
;                     if (t + 1 < 32) { nA = *(const f32x4*)(pp + (t + 1) * 384); nB = *(const f32x4*)(pp + (t + 1) * 384 + 4); nr = *(const f32x2*)(pp + (t + 1) * 384 + 8); nv = pv[(t + 1) * 16]; }
;                     float S0 = S.x, S1 = S.y;
;                     float d = S0 * a2.x; d = __builtin_fmaf(S1, a2.y, d);
;                     float t0 = S0 * w2.x; t0 = __builtin_fmaf(v, k2.x, t0); asm volatile("" : "+v"(t0));
;                     float t1 = S1 * w2.y; t1 = __builtin_fmaf(v, k2.y, t1); asm volatile("" : "+v"(t1));
;                     float yprev; const float sa = wkv_reduce(d, ep, yprev);
;                     S0 = __builtin_fmaf(sa, b2.x, t0); asm volatile("" : "+v"(S0));
;                     S1 = __builtin_fmaf(sa, b2.y, t1); asm volatile("" : "+v"(S1));
;                     ep = S0 * r2.x; ep = __builtin_fmaf(S1, r2.y, ep);
;                     S.x = S0; S.y = S1;
;                     if (t >= 1) { const bool hit = oddrow && ((lane & 15) == ((t - 1) & 15)); if (t <= 16) yk0 = hit ? yprev : yk0; else yk1 = hit ? yprev : yk1; }
;                 }
;                 { float ylast; (void)wkv_reduce(0.f, ep, ylast); yk1 = (oddrow && (lane & 15) == 15) ? ylast : yk1; }
;                 if (oddrow) { sY[bi * 512 + (lane & 15) * 16 + il] = yk0; sY[bi * 512 + (16 + (lane & 15)) * 16 + il] = yk1; }
	v_pk_mul_f32 v[150:151], v[142:143], v[190:191]
	v_pk_fma_f32 v[150:151], v[144:145], v[198:199], v[150:151]
	v_pk_mul_f32 v[152:153], v[142:143], v[236:237]
	v_add_f32_e32 v154, v150, v151
	v_pk_fma_f32 v[152:153], v[144:145], v[238:239], v[152:153]
	v_pk_mul_f32 v[146:147], v[142:143], v[192:193]
	v_add_f32_dpp v154, v154, v154 quad_perm:[1,0,3,2] row_mask:0xf bank_mask:0xf bound_ctrl:1
	v_pk_mul_f32 v[148:149], v[144:145], v[200:201]
	v_add_f32_e32 v169, v152, v153
	v_add_f32_dpp v154, v154, v154 quad_perm:[2,3,0,1] row_mask:0xf bank_mask:0xf bound_ctrl:1
	v_pk_fma_f32 v[146:147], v[242:243], v[196:197], v[146:147] op_sel:[0,0,0] op_sel_hi:[0,1,1]
	v_pk_fma_f32 v[148:149], v[242:243], v[204:205], v[148:149] op_sel:[0,0,0] op_sel_hi:[0,1,1]
	v_add_f32_dpp v154, v154, v154 row_half_mirror row_mask:0xf bank_mask:0xf bound_ctrl:1
	s_nop 1
	v_add_f32_dpp v154, v154, v154 row_mirror row_mask:0xf bank_mask:0xf bound_ctrl:1
	v_pk_fma_f32 v[146:147], v[154:155], v[194:195], v[146:147] op_sel_hi:[0,1,1]
	v_pk_fma_f32 v[148:149], v[154:155], v[202:203], v[148:149] op_sel_hi:[0,1,1]
	s_waitcnt lgkmcnt(0)
	v_pk_mul_f32 v[150:151], v[146:147], v[206:207]
	v_pk_fma_f32 v[150:151], v[148:149], v[214:215], v[150:151]
	v_pk_mul_f32 v[152:153], v[146:147], v[228:229]
	v_add_f32_e32 v154, v150, v151
	v_pk_fma_f32 v[152:153], v[148:149], v[230:231], v[152:153]
	v_pk_mul_f32 v[142:143], v[146:147], v[208:209]
	v_add_f32_dpp v154, v154, v154 quad_perm:[1,0,3,2] row_mask:0xf bank_mask:0xf bound_ctrl:1
	v_pk_mul_f32 v[144:145], v[148:149], v[216:217]
	v_add_f32_e32 v170, v152, v153
	v_add_f32_dpp v154, v154, v154 quad_perm:[2,3,0,1] row_mask:0xf bank_mask:0xf bound_ctrl:1
	v_pk_fma_f32 v[142:143], v[242:243], v[212:213], v[142:143] op_sel:[1,0,0] op_sel_hi:[1,1,1]
	v_pk_fma_f32 v[144:145], v[242:243], v[220:221], v[144:145] op_sel:[1,0,0] op_sel_hi:[1,1,1]
	v_add_f32_dpp v154, v154, v154 row_half_mirror row_mask:0xf bank_mask:0xf bound_ctrl:1
	s_nop 1
	v_add_f32_dpp v154, v154, v154 row_mirror row_mask:0xf bank_mask:0xf bound_ctrl:1
	v_pk_fma_f32 v[142:143], v[154:155], v[210:211], v[142:143] op_sel_hi:[0,1,1]
	v_pk_fma_f32 v[144:145], v[154:155], v[218:219], v[144:145] op_sel_hi:[0,1,1]
	v_pk_mul_f32 v[152:153], v[142:143], v[232:233]
	v_pk_fma_f32 v[152:153], v[144:145], v[234:235], v[152:153]
	s_nop 0
	v_add_f32_e32 v171, v152, v153
	v_add_f32_dpp v172, v156, v156 row_ror:8 row_mask:0xf bank_mask:0x3
	v_add_f32_dpp v172, v164, v164 row_ror:8 row_mask:0xf bank_mask:0xc
	v_add_f32_dpp v173, v157, v157 row_ror:8 row_mask:0xf bank_mask:0x3
	v_add_f32_dpp v173, v165, v165 row_ror:8 row_mask:0xf bank_mask:0xc
	v_add_f32_dpp v174, v158, v158 row_ror:8 row_mask:0xf bank_mask:0x3
	v_add_f32_dpp v174, v166, v166 row_ror:8 row_mask:0xf bank_mask:0xc
	v_add_f32_dpp v175, v159, v159 row_ror:8 row_mask:0xf bank_mask:0x3
	v_add_f32_dpp v175, v167, v167 row_ror:8 row_mask:0xf bank_mask:0xc
	v_add_f32_dpp v176, v160, v160 row_ror:8 row_mask:0xf bank_mask:0x3
	v_add_f32_dpp v176, v168, v168 row_ror:8 row_mask:0xf bank_mask:0xc
	v_add_f32_dpp v177, v161, v161 row_ror:8 row_mask:0xf bank_mask:0x3
	v_add_f32_dpp v177, v169, v169 row_ror:8 row_mask:0xf bank_mask:0xc
	v_add_f32_dpp v178, v162, v162 row_ror:8 row_mask:0xf bank_mask:0x3
	v_add_f32_dpp v178, v170, v170 row_ror:8 row_mask:0xf bank_mask:0xc
	v_add_f32_dpp v179, v163, v163 row_ror:8 row_mask:0xf bank_mask:0x3
	v_add_f32_dpp v179, v171, v171 row_ror:8 row_mask:0xf bank_mask:0xc
	v_add_f32_dpp v156, v172, v172 row_half_mirror row_mask:0xf bank_mask:0x5
	v_add_f32_dpp v156, v176, v176 row_half_mirror row_mask:0xf bank_mask:0xa
	v_add_f32_dpp v157, v173, v173 row_half_mirror row_mask:0xf bank_mask:0x5
	v_add_f32_dpp v157, v177, v177 row_half_mirror row_mask:0xf bank_mask:0xa
	v_add_f32_dpp v158, v174, v174 row_half_mirror row_mask:0xf bank_mask:0x5
	v_add_f32_dpp v158, v178, v178 row_half_mirror row_mask:0xf bank_mask:0xa
	v_add_f32_dpp v159, v175, v175 row_half_mirror row_mask:0xf bank_mask:0x5
	v_add_f32_dpp v159, v179, v179 row_half_mirror row_mask:0xf bank_mask:0xa
	v_cndmask_b32_e64 v176, v158, v156, s[14:15]
	v_cndmask_b32_e64 v177, v159, v157, s[14:15]
	v_cndmask_b32_e64 v178, v156, v158, s[14:15]
	v_cndmask_b32_e64 v179, v157, v159, s[14:15]
	v_add_f32_dpp v172, v176, v178 quad_perm:[2,3,0,1] row_mask:0xf bank_mask:0xf
	v_add_f32_dpp v173, v177, v179 quad_perm:[2,3,0,1] row_mask:0xf bank_mask:0xf
	v_cndmask_b32_e64 v176, v173, v172, s[16:17]
	v_cndmask_b32_e64 v178, v172, v173, s[16:17]
	s_nop 0
	v_add_f32_dpp v181, v176, v178 quad_perm:[1,0,3,2] row_mask:0xf bank_mask:0xf
	ds_write2st64_b32 v187, v180, v181 offset0:8 offset1:12
